# baseline (speedup 1.0000x reference)
; __device__ __forceinline__ float wkv_reduce(float x, float y, float& zy) {
;     auto f = __builtin_amdgcn_permlane16_swap(__float_as_uint(x), __float_as_uint(y), false, false);
;     float z = __uint_as_float(f[0]) + __uint_as_float(f[1]);
;     z += dpp_f(z, 0); z += dpp_f(z, 1); z += dpp_f(z, 2); z += dpp_f(z, 3);
;     zy = z;
;     const int zi = __builtin_bit_cast(int, z);
;     return __builtin_bit_cast(float, __builtin_amdgcn_update_dpp(zi, zi, 0x142, 0xA, 0xF, false));
; }
; __device__ __forceinline__ void wkv_phase(const WkvT& W, unsigned char* lds) {
;     ...
;                 const float* pp = sP + bo + jj * 12;
;                 const float* pv = sV + bi * 512 + il;
;                 f32x4 nA = *(const f32x4*)pp, nB = *(const f32x4*)(pp + 4); f32x2 nr = *(const f32x2*)(pp + 8); float nv = pv[0];
;                 float yk0 = 0.f, yk1 = 0.f, ep = 0.f;
;                 const bool oddrow = (lane & 16) != 0;
; #pragma unroll
;                 for (int t = 0; t < 32; ++t) {
;                     const f32x2 a2 = {nA[0], nA[1]}, w2 = {nA[2], nA[3]}, b2 = {nB[0], nB[1]}, k2 = {nB[2], nB[3]}, r2 = nr; const float v = nv;
;                     if (t + 1 < 32) { nA = *(const f32x4*)(pp + (t + 1) * 384); nB = *(const f32x4*)(pp + (t + 1) * 384 + 4); nr = *(const f32x2*)(pp + (t + 1) * 384 + 8); nv = pv[(t + 1) * 16]; }
;                     float S0 = S.x, S1 = S.y;
;                     float d = S0 * a2.x; d = __builtin_fmaf(S1, a2.y, d);
;                     float t0 = S0 * w2.x; t0 = __builtin_fmaf(v, k2.x, t0); asm volatile("" : "+v"(t0));
;                     float t1 = S1 * w2.y; t1 = __builtin_fmaf(v, k2.y, t1); asm volatile("" : "+v"(t1));
;                     float yprev; const float sa = wkv_reduce(d, ep, yprev);
;                     S0 = __builtin_fmaf(sa, b2.x, t0); asm volatile("" : "+v"(S0));
;                     S1 = __builtin_fmaf(sa, b2.y, t1); asm volatile("" : "+v"(S1));
;                     ep = S0 * r2.x; ep = __builtin_fmaf(S1, r2.y, ep);
;                     S.x = S0; S.y = S1;
;                     if (t >= 1) { const bool hit = oddrow && ((lane & 15) == ((t - 1) & 15)); if (t <= 16) yk0 = hit ? yprev : yk0; else yk1 = hit ? yprev : yk1; }
.LBB0_1624:
	s_or_b64 exec, exec, s[46:47]
	v_add_u32_e32 v232, 0x400, v21
	v_mov_b32_e32 v145, 0
	v_mov_b32_e32 v148, 0
	ds_read_b128 v[160:163], v19
	ds_read_b128 v[164:167], v19 offset:16
	ds_read_b64 v[168:169], v19 offset:32
	ds_read2_b32 v[224:225], v21 offset0:0 offset1:16
	ds_read_b128 v[176:179], v19 offset:1536
	ds_read_b128 v[180:183], v19 offset:1552
	ds_read_b64 v[184:185], v19 offset:1568
	ds_read_b128 v[192:195], v19 offset:3072
	ds_read_b128 v[196:199], v19 offset:3088
	ds_read_b64 v[200:201], v19 offset:3104
	ds_read2_b32 v[226:227], v21 offset0:32 offset1:48
	s_waitcnt lgkmcnt(7)
	v_mul_f32_e32 v144, v140, v160
	v_fmac_f32_e32 v144, v141, v161
	v_pk_mul_f32 v[150:151], v[140:141], v[162:163]
	s_nop 0
	v_permlane16_swap_b32_e32 v144, v145
	v_add_f32_e32 v144, v144, v145
	v_pk_fma_f32 v[150:151], v[224:225], v[166:167], v[150:151] op_sel:[0,0,0] op_sel_hi:[0,1,1]
	s_nop 0
	v_add_f32_dpp v144, v144, v144 quad_perm:[1,0,3,2] row_mask:0xf bank_mask:0xf bound_ctrl:1
	ds_read_b128 v[208:211], v19 offset:4608
	ds_read_b128 v[212:215], v19 offset:4624
	v_add_f32_dpp v144, v144, v144 quad_perm:[2,3,0,1] row_mask:0xf bank_mask:0xf bound_ctrl:1
	ds_read_b64 v[216:217], v19 offset:4640
	s_nop 0
	v_add_f32_dpp v144, v144, v144 row_half_mirror row_mask:0xf bank_mask:0xf bound_ctrl:1
	s_waitcnt lgkmcnt(7)
	s_nop 0
	v_add_f32_dpp v144, v144, v144 row_mirror row_mask:0xf bank_mask:0xf bound_ctrl:1
	s_nop 1
	v_mov_b32_dpp v144, v144 row_bcast:15 row_mask:0xa bank_mask:0xf
	v_pk_fma_f32 v[150:151], v[144:145], v[164:165], v[150:151] op_sel_hi:[0,1,1]
	v_mul_f32_e32 v144, v150, v176
	v_mul_f32_e32 v145, v150, v168
	v_fmac_f32_e32 v144, v151, v177
	v_fmac_f32_e32 v145, v151, v169
	v_pk_mul_f32 v[152:153], v[150:151], v[178:179]
	s_nop 0
	v_permlane16_swap_b32_e32 v144, v145
	v_add_f32_e32 v144, v144, v145
	v_pk_fma_f32 v[152:153], v[224:225], v[182:183], v[152:153] op_sel:[1,0,0] op_sel_hi:[1,1,1]
	s_nop 0
	v_add_f32_dpp v144, v144, v144 quad_perm:[1,0,3,2] row_mask:0xf bank_mask:0xf bound_ctrl:1
	ds_read_b128 v[160:163], v19 offset:6144
	ds_read_b128 v[164:167], v19 offset:6160
	v_add_f32_dpp v144, v144, v144 quad_perm:[2,3,0,1] row_mask:0xf bank_mask:0xf bound_ctrl:1
	ds_read_b64 v[168:169], v19 offset:6176
	ds_read2_b32 v[228:229], v21 offset0:64 offset1:80
	v_add_f32_dpp v144, v144, v144 row_half_mirror row_mask:0xf bank_mask:0xf bound_ctrl:1
	s_waitcnt lgkmcnt(7)
	s_nop 0
	v_add_f32_dpp v144, v144, v144 row_mirror row_mask:0xf bank_mask:0xf bound_ctrl:1
	v_cndmask_b32_e64 v146, v146, v144, s[10:11]
	s_nop 0
	v_mov_b32_dpp v144, v144 row_bcast:15 row_mask:0xa bank_mask:0xf
	v_pk_fma_f32 v[152:153], v[144:145], v[180:181], v[152:153] op_sel_hi:[0,1,1]
	v_mul_f32_e32 v144, v152, v192
	v_mul_f32_e32 v145, v152, v184
	v_fmac_f32_e32 v144, v153, v193
	v_fmac_f32_e32 v145, v153, v185
	v_pk_mul_f32 v[150:151], v[152:153], v[194:195]
	s_nop 0
	v_permlane16_swap_b32_e32 v144, v145
	v_add_f32_e32 v144, v144, v145
	v_pk_fma_f32 v[150:151], v[226:227], v[198:199], v[150:151] op_sel:[0,0,0] op_sel_hi:[0,1,1]
	s_nop 0
	v_add_f32_dpp v144, v144, v144 quad_perm:[1,0,3,2] row_mask:0xf bank_mask:0xf bound_ctrl:1
	ds_read_b128 v[176:179], v19 offset:7680
	ds_read_b128 v[180:183], v19 offset:7696
	v_add_f32_dpp v144, v144, v144 quad_perm:[2,3,0,1] row_mask:0xf bank_mask:0xf bound_ctrl:1
	ds_read_b64 v[184:185], v19 offset:7712
	s_nop 0
	v_add_f32_dpp v144, v144, v144 row_half_mirror row_mask:0xf bank_mask:0xf bound_ctrl:1
	s_waitcnt lgkmcnt(7)
	s_nop 0
	v_add_f32_dpp v144, v144, v144 row_mirror row_mask:0xf bank_mask:0xf bound_ctrl:1
	v_cndmask_b32_e64 v146, v146, v144, s[12:13]
	s_nop 0
	v_mov_b32_dpp v144, v144 row_bcast:15 row_mask:0xa bank_mask:0xf
	v_pk_fma_f32 v[150:151], v[144:145], v[196:197], v[150:151] op_sel_hi:[0,1,1]
	v_mul_f32_e32 v144, v150, v208
	v_mul_f32_e32 v145, v150, v200
	v_fmac_f32_e32 v144, v151, v209
	v_fmac_f32_e32 v145, v151, v201
	v_pk_mul_f32 v[152:153], v[150:151], v[210:211]
	s_nop 0
	v_permlane16_swap_b32_e32 v144, v145
	v_add_f32_e32 v144, v144, v145
	v_pk_fma_f32 v[152:153], v[226:227], v[214:215], v[152:153] op_sel:[1,0,0] op_sel_hi:[1,1,1]
	s_nop 0
	v_add_f32_dpp v144, v144, v144 quad_perm:[1,0,3,2] row_mask:0xf bank_mask:0xf bound_ctrl:1
	ds_read_b128 v[192:195], v19 offset:9216
	ds_read_b128 v[196:199], v19 offset:9232
	v_add_f32_dpp v144, v144, v144 quad_perm:[2,3,0,1] row_mask:0xf bank_mask:0xf bound_ctrl:1
	ds_read_b64 v[200:201], v19 offset:9248
	ds_read2_b32 v[230:231], v21 offset0:96 offset1:112
	v_add_f32_dpp v144, v144, v144 row_half_mirror row_mask:0xf bank_mask:0xf bound_ctrl:1
	s_waitcnt lgkmcnt(7)
	s_nop 0
	v_add_f32_dpp v144, v144, v144 row_mirror row_mask:0xf bank_mask:0xf bound_ctrl:1
	v_cndmask_b32_e64 v146, v146, v144, s[14:15]
	s_nop 0
	v_mov_b32_dpp v144, v144 row_bcast:15 row_mask:0xa bank_mask:0xf
	v_pk_fma_f32 v[152:153], v[144:145], v[212:213], v[152:153] op_sel_hi:[0,1,1]
	v_mul_f32_e32 v144, v152, v160
	v_mul_f32_e32 v145, v152, v216
	v_fmac_f32_e32 v144, v153, v161
	v_fmac_f32_e32 v145, v153, v217
	v_pk_mul_f32 v[150:151], v[152:153], v[162:163]
	s_nop 0
	v_permlane16_swap_b32_e32 v144, v145
	v_add_f32_e32 v144, v144, v145
	v_pk_fma_f32 v[150:151], v[228:229], v[166:167], v[150:151] op_sel:[0,0,0] op_sel_hi:[0,1,1]
	s_nop 0
	v_add_f32_dpp v144, v144, v144 quad_perm:[1,0,3,2] row_mask:0xf bank_mask:0xf bound_ctrl:1
	ds_read_b128 v[208:211], v19 offset:10752
	ds_read_b128 v[212:215], v19 offset:10768
	v_add_f32_dpp v144, v144, v144 quad_perm:[2,3,0,1] row_mask:0xf bank_mask:0xf bound_ctrl:1
	ds_read_b64 v[216:217], v19 offset:10784
	s_nop 0
	v_add_f32_dpp v144, v144, v144 row_half_mirror row_mask:0xf bank_mask:0xf bound_ctrl:1
	s_waitcnt lgkmcnt(7)
; __device__ __forceinline__ float wkv_reduce(float x, float y, float& zy) {
;     auto f = __builtin_amdgcn_permlane16_swap(__float_as_uint(x), __float_as_uint(y), false, false);
;     float z = __uint_as_float(f[0]) + __uint_as_float(f[1]);
;     z += dpp_f(z, 0); z += dpp_f(z, 1); z += dpp_f(z, 2); z += dpp_f(z, 3);
;     zy = z;
;     const int zi = __builtin_bit_cast(int, z);
;     return __builtin_bit_cast(float, __builtin_amdgcn_update_dpp(zi, zi, 0x142, 0xA, 0xF, false));
; }
; __device__ __forceinline__ void wkv_phase(const WkvT& W, unsigned char* lds) {
;     ...
;                 for (int t = 0; t < 32; ++t) {
;                     const f32x2 a2 = {nA[0], nA[1]}, w2 = {nA[2], nA[3]}, b2 = {nB[0], nB[1]}, k2 = {nB[2], nB[3]}, r2 = nr; const float v = nv;
;                     if (t + 1 < 32) { nA = *(const f32x4*)(pp + (t + 1) * 384); nB = *(const f32x4*)(pp + (t + 1) * 384 + 4); nr = *(const f32x2*)(pp + (t + 1) * 384 + 8); nv = pv[(t + 1) * 16]; }
;                     float S0 = S.x, S1 = S.y;
;                     float d = S0 * a2.x; d = __builtin_fmaf(S1, a2.y, d);
;                     float t0 = S0 * w2.x; t0 = __builtin_fmaf(v, k2.x, t0); asm volatile("" : "+v"(t0));
;                     float t1 = S1 * w2.y; t1 = __builtin_fmaf(v, k2.y, t1); asm volatile("" : "+v"(t1));
;                     float yprev; const float sa = wkv_reduce(d, ep, yprev);
;                     S0 = __builtin_fmaf(sa, b2.x, t0); asm volatile("" : "+v"(S0));
;                     S1 = __builtin_fmaf(sa, b2.y, t1); asm volatile("" : "+v"(S1));
;                     ep = S0 * r2.x; ep = __builtin_fmaf(S1, r2.y, ep);
;                     S.x = S0; S.y = S1;
;                     if (t >= 1) { const bool hit = oddrow && ((lane & 15) == ((t - 1) & 15)); if (t <= 16) yk0 = hit ? yprev : yk0; else yk1 = hit ? yprev : yk1; }
	s_nop 0
	v_add_f32_dpp v144, v144, v144 row_mirror row_mask:0xf bank_mask:0xf bound_ctrl:1
	v_cndmask_b32_e64 v146, v146, v144, s[16:17]
	s_nop 0
	v_mov_b32_dpp v144, v144 row_bcast:15 row_mask:0xa bank_mask:0xf
	v_pk_fma_f32 v[150:151], v[144:145], v[164:165], v[150:151] op_sel_hi:[0,1,1]
	v_mul_f32_e32 v144, v150, v176
	v_mul_f32_e32 v145, v150, v168
	v_fmac_f32_e32 v144, v151, v177
	v_fmac_f32_e32 v145, v151, v169
	v_pk_mul_f32 v[152:153], v[150:151], v[178:179]
	s_nop 0
	v_permlane16_swap_b32_e32 v144, v145
	v_add_f32_e32 v144, v144, v145
	v_pk_fma_f32 v[152:153], v[228:229], v[182:183], v[152:153] op_sel:[1,0,0] op_sel_hi:[1,1,1]
	s_nop 0
	v_add_f32_dpp v144, v144, v144 quad_perm:[1,0,3,2] row_mask:0xf bank_mask:0xf bound_ctrl:1
	ds_read_b128 v[160:163], v19 offset:12288
	ds_read_b128 v[164:167], v19 offset:12304
	v_add_f32_dpp v144, v144, v144 quad_perm:[2,3,0,1] row_mask:0xf bank_mask:0xf bound_ctrl:1
	ds_read_b64 v[168:169], v19 offset:12320
	ds_read2_b32 v[224:225], v21 offset0:128 offset1:144
	v_add_f32_dpp v144, v144, v144 row_half_mirror row_mask:0xf bank_mask:0xf bound_ctrl:1
	s_waitcnt lgkmcnt(7)
	s_nop 0
	v_add_f32_dpp v144, v144, v144 row_mirror row_mask:0xf bank_mask:0xf bound_ctrl:1
	v_cndmask_b32_e64 v146, v146, v144, s[18:19]
	s_nop 0
	v_mov_b32_dpp v144, v144 row_bcast:15 row_mask:0xa bank_mask:0xf
	v_pk_fma_f32 v[152:153], v[144:145], v[180:181], v[152:153] op_sel_hi:[0,1,1]
	v_mul_f32_e32 v144, v152, v192
	v_mul_f32_e32 v145, v152, v184
	v_fmac_f32_e32 v144, v153, v193
	v_fmac_f32_e32 v145, v153, v185
	v_pk_mul_f32 v[150:151], v[152:153], v[194:195]
	s_nop 0
	v_permlane16_swap_b32_e32 v144, v145
	v_add_f32_e32 v144, v144, v145
	v_pk_fma_f32 v[150:151], v[230:231], v[198:199], v[150:151] op_sel:[0,0,0] op_sel_hi:[0,1,1]
	s_nop 0
	v_add_f32_dpp v144, v144, v144 quad_perm:[1,0,3,2] row_mask:0xf bank_mask:0xf bound_ctrl:1
	ds_read_b128 v[176:179], v19 offset:13824
	ds_read_b128 v[180:183], v19 offset:13840
	v_add_f32_dpp v144, v144, v144 quad_perm:[2,3,0,1] row_mask:0xf bank_mask:0xf bound_ctrl:1
	ds_read_b64 v[184:185], v19 offset:13856
	s_nop 0
	v_add_f32_dpp v144, v144, v144 row_half_mirror row_mask:0xf bank_mask:0xf bound_ctrl:1
	s_waitcnt lgkmcnt(7)
	s_nop 0
	v_add_f32_dpp v144, v144, v144 row_mirror row_mask:0xf bank_mask:0xf bound_ctrl:1
	v_cndmask_b32_e64 v146, v146, v144, s[20:21]
	s_nop 0
	v_mov_b32_dpp v144, v144 row_bcast:15 row_mask:0xa bank_mask:0xf
	v_pk_fma_f32 v[150:151], v[144:145], v[196:197], v[150:151] op_sel_hi:[0,1,1]
	v_mul_f32_e32 v144, v150, v208
	v_mul_f32_e32 v145, v150, v200
	v_fmac_f32_e32 v144, v151, v209
	v_fmac_f32_e32 v145, v151, v201
	v_pk_mul_f32 v[152:153], v[150:151], v[210:211]
	s_nop 0
	v_permlane16_swap_b32_e32 v144, v145
	v_add_f32_e32 v144, v144, v145
	v_pk_fma_f32 v[152:153], v[230:231], v[214:215], v[152:153] op_sel:[1,0,0] op_sel_hi:[1,1,1]
	s_nop 0
	v_add_f32_dpp v144, v144, v144 quad_perm:[1,0,3,2] row_mask:0xf bank_mask:0xf bound_ctrl:1
	ds_read_b128 v[192:195], v19 offset:15360
	ds_read_b128 v[196:199], v19 offset:15376
	v_add_f32_dpp v144, v144, v144 quad_perm:[2,3,0,1] row_mask:0xf bank_mask:0xf bound_ctrl:1
	ds_read_b64 v[200:201], v19 offset:15392
	ds_read2_b32 v[226:227], v21 offset0:160 offset1:176
	v_add_f32_dpp v144, v144, v144 row_half_mirror row_mask:0xf bank_mask:0xf bound_ctrl:1
	s_waitcnt lgkmcnt(7)
	s_nop 0
	v_add_f32_dpp v144, v144, v144 row_mirror row_mask:0xf bank_mask:0xf bound_ctrl:1
	v_cndmask_b32_e64 v146, v146, v144, s[22:23]
	s_nop 0
	v_mov_b32_dpp v144, v144 row_bcast:15 row_mask:0xa bank_mask:0xf
	v_pk_fma_f32 v[152:153], v[144:145], v[212:213], v[152:153] op_sel_hi:[0,1,1]
	v_mul_f32_e32 v144, v152, v160
	v_mul_f32_e32 v145, v152, v216
	v_fmac_f32_e32 v144, v153, v161
	v_fmac_f32_e32 v145, v153, v217
	v_pk_mul_f32 v[150:151], v[152:153], v[162:163]
	s_nop 0
	v_permlane16_swap_b32_e32 v144, v145
	v_add_f32_e32 v144, v144, v145
	v_pk_fma_f32 v[150:151], v[224:225], v[166:167], v[150:151] op_sel:[0,0,0] op_sel_hi:[0,1,1]
	s_nop 0
	v_add_f32_dpp v144, v144, v144 quad_perm:[1,0,3,2] row_mask:0xf bank_mask:0xf bound_ctrl:1
	ds_read_b128 v[208:211], v19 offset:16896
	ds_read_b128 v[212:215], v19 offset:16912
	v_add_f32_dpp v144, v144, v144 quad_perm:[2,3,0,1] row_mask:0xf bank_mask:0xf bound_ctrl:1
	ds_read_b64 v[216:217], v19 offset:16928
	s_nop 0
	v_add_f32_dpp v144, v144, v144 row_half_mirror row_mask:0xf bank_mask:0xf bound_ctrl:1
	s_waitcnt lgkmcnt(7)
	s_nop 0
	v_add_f32_dpp v144, v144, v144 row_mirror row_mask:0xf bank_mask:0xf bound_ctrl:1
	v_cndmask_b32_e64 v146, v146, v144, s[24:25]
	s_nop 0
	v_mov_b32_dpp v144, v144 row_bcast:15 row_mask:0xa bank_mask:0xf
	v_pk_fma_f32 v[150:151], v[144:145], v[164:165], v[150:151] op_sel_hi:[0,1,1]
	v_mul_f32_e32 v144, v150, v176
	v_mul_f32_e32 v145, v150, v168
	v_fmac_f32_e32 v144, v151, v177
	v_fmac_f32_e32 v145, v151, v169
	v_pk_mul_f32 v[152:153], v[150:151], v[178:179]
	s_nop 0
	v_permlane16_swap_b32_e32 v144, v145
	v_add_f32_e32 v144, v144, v145
	v_pk_fma_f32 v[152:153], v[224:225], v[182:183], v[152:153] op_sel:[1,0,0] op_sel_hi:[1,1,1]
	s_nop 0
	v_add_f32_dpp v144, v144, v144 quad_perm:[1,0,3,2] row_mask:0xf bank_mask:0xf bound_ctrl:1
	ds_read_b128 v[160:163], v19 offset:18432
	ds_read_b128 v[164:167], v19 offset:18448
	v_add_f32_dpp v144, v144, v144 quad_perm:[2,3,0,1] row_mask:0xf bank_mask:0xf bound_ctrl:1
	ds_read_b64 v[168:169], v19 offset:18464
	ds_read2_b32 v[228:229], v21 offset0:192 offset1:208
	v_add_f32_dpp v144, v144, v144 row_half_mirror row_mask:0xf bank_mask:0xf bound_ctrl:1
	s_waitcnt lgkmcnt(7)
; __device__ __forceinline__ float wkv_reduce(float x, float y, float& zy) {
;     auto f = __builtin_amdgcn_permlane16_swap(__float_as_uint(x), __float_as_uint(y), false, false);
;     float z = __uint_as_float(f[0]) + __uint_as_float(f[1]);
;     z += dpp_f(z, 0); z += dpp_f(z, 1); z += dpp_f(z, 2); z += dpp_f(z, 3);
;     zy = z;
;     const int zi = __builtin_bit_cast(int, z);
;     return __builtin_bit_cast(float, __builtin_amdgcn_update_dpp(zi, zi, 0x142, 0xA, 0xF, false));
; }
; __device__ __forceinline__ void wkv_phase(const WkvT& W, unsigned char* lds) {
;     ...
;                 for (int t = 0; t < 32; ++t) {
;                     const f32x2 a2 = {nA[0], nA[1]}, w2 = {nA[2], nA[3]}, b2 = {nB[0], nB[1]}, k2 = {nB[2], nB[3]}, r2 = nr; const float v = nv;
;                     if (t + 1 < 32) { nA = *(const f32x4*)(pp + (t + 1) * 384); nB = *(const f32x4*)(pp + (t + 1) * 384 + 4); nr = *(const f32x2*)(pp + (t + 1) * 384 + 8); nv = pv[(t + 1) * 16]; }
;                     float S0 = S.x, S1 = S.y;
;                     float d = S0 * a2.x; d = __builtin_fmaf(S1, a2.y, d);
;                     float t0 = S0 * w2.x; t0 = __builtin_fmaf(v, k2.x, t0); asm volatile("" : "+v"(t0));
;                     float t1 = S1 * w2.y; t1 = __builtin_fmaf(v, k2.y, t1); asm volatile("" : "+v"(t1));
;                     float yprev; const float sa = wkv_reduce(d, ep, yprev);
;                     S0 = __builtin_fmaf(sa, b2.x, t0); asm volatile("" : "+v"(S0));
;                     S1 = __builtin_fmaf(sa, b2.y, t1); asm volatile("" : "+v"(S1));
;                     ep = S0 * r2.x; ep = __builtin_fmaf(S1, r2.y, ep);
;                     S.x = S0; S.y = S1;
;                     if (t >= 1) { const bool hit = oddrow && ((lane & 15) == ((t - 1) & 15)); if (t <= 16) yk0 = hit ? yprev : yk0; else yk1 = hit ? yprev : yk1; }
	s_nop 0
	v_add_f32_dpp v144, v144, v144 row_mirror row_mask:0xf bank_mask:0xf bound_ctrl:1
	v_cndmask_b32_e64 v146, v146, v144, s[26:27]
	s_nop 0
	v_mov_b32_dpp v144, v144 row_bcast:15 row_mask:0xa bank_mask:0xf
	v_pk_fma_f32 v[152:153], v[144:145], v[180:181], v[152:153] op_sel_hi:[0,1,1]
	v_mul_f32_e32 v144, v152, v192
	v_mul_f32_e32 v145, v152, v184
	v_fmac_f32_e32 v144, v153, v193
	v_fmac_f32_e32 v145, v153, v185
	v_pk_mul_f32 v[150:151], v[152:153], v[194:195]
	s_nop 0
	v_permlane16_swap_b32_e32 v144, v145
	v_add_f32_e32 v144, v144, v145
	v_pk_fma_f32 v[150:151], v[226:227], v[198:199], v[150:151] op_sel:[0,0,0] op_sel_hi:[0,1,1]
	s_nop 0
	v_add_f32_dpp v144, v144, v144 quad_perm:[1,0,3,2] row_mask:0xf bank_mask:0xf bound_ctrl:1
	ds_read_b128 v[176:179], v19 offset:19968
	ds_read_b128 v[180:183], v19 offset:19984
	v_add_f32_dpp v144, v144, v144 quad_perm:[2,3,0,1] row_mask:0xf bank_mask:0xf bound_ctrl:1
	ds_read_b64 v[184:185], v19 offset:20000
	s_nop 0
	v_add_f32_dpp v144, v144, v144 row_half_mirror row_mask:0xf bank_mask:0xf bound_ctrl:1
	s_waitcnt lgkmcnt(7)
	s_nop 0
	v_add_f32_dpp v144, v144, v144 row_mirror row_mask:0xf bank_mask:0xf bound_ctrl:1
	v_cndmask_b32_e64 v146, v146, v144, s[28:29]
	s_nop 0
	v_mov_b32_dpp v144, v144 row_bcast:15 row_mask:0xa bank_mask:0xf
	v_pk_fma_f32 v[150:151], v[144:145], v[196:197], v[150:151] op_sel_hi:[0,1,1]
	v_mul_f32_e32 v144, v150, v208
	v_mul_f32_e32 v145, v150, v200
	v_fmac_f32_e32 v144, v151, v209
	v_fmac_f32_e32 v145, v151, v201
	v_pk_mul_f32 v[152:153], v[150:151], v[210:211]
	s_nop 0
	v_permlane16_swap_b32_e32 v144, v145
	v_add_f32_e32 v144, v144, v145
	v_pk_fma_f32 v[152:153], v[226:227], v[214:215], v[152:153] op_sel:[1,0,0] op_sel_hi:[1,1,1]
	s_nop 0
	v_add_f32_dpp v144, v144, v144 quad_perm:[1,0,3,2] row_mask:0xf bank_mask:0xf bound_ctrl:1
	ds_read_b128 v[192:195], v19 offset:21504
	ds_read_b128 v[196:199], v19 offset:21520
	v_add_f32_dpp v144, v144, v144 quad_perm:[2,3,0,1] row_mask:0xf bank_mask:0xf bound_ctrl:1
	ds_read_b64 v[200:201], v19 offset:21536
	ds_read2_b32 v[230:231], v21 offset0:224 offset1:240
	v_add_f32_dpp v144, v144, v144 row_half_mirror row_mask:0xf bank_mask:0xf bound_ctrl:1
	s_waitcnt lgkmcnt(7)
	s_nop 0
	v_add_f32_dpp v144, v144, v144 row_mirror row_mask:0xf bank_mask:0xf bound_ctrl:1
	v_cndmask_b32_e64 v146, v146, v144, s[30:31]
	s_nop 0
	v_mov_b32_dpp v144, v144 row_bcast:15 row_mask:0xa bank_mask:0xf
	v_pk_fma_f32 v[152:153], v[144:145], v[212:213], v[152:153] op_sel_hi:[0,1,1]
	v_mul_f32_e32 v144, v152, v160
	v_mul_f32_e32 v145, v152, v216
	v_fmac_f32_e32 v144, v153, v161
	v_fmac_f32_e32 v145, v153, v217
	v_pk_mul_f32 v[150:151], v[152:153], v[162:163]
	s_nop 0
	v_permlane16_swap_b32_e32 v144, v145
	v_add_f32_e32 v144, v144, v145
	v_pk_fma_f32 v[150:151], v[228:229], v[166:167], v[150:151] op_sel:[0,0,0] op_sel_hi:[0,1,1]
	s_nop 0
	v_add_f32_dpp v144, v144, v144 quad_perm:[1,0,3,2] row_mask:0xf bank_mask:0xf bound_ctrl:1
	ds_read_b128 v[208:211], v19 offset:23040
	ds_read_b128 v[212:215], v19 offset:23056
	v_add_f32_dpp v144, v144, v144 quad_perm:[2,3,0,1] row_mask:0xf bank_mask:0xf bound_ctrl:1
	ds_read_b64 v[216:217], v19 offset:23072
	s_nop 0
	v_add_f32_dpp v144, v144, v144 row_half_mirror row_mask:0xf bank_mask:0xf bound_ctrl:1
	s_waitcnt lgkmcnt(7)
	s_nop 0
	v_add_f32_dpp v144, v144, v144 row_mirror row_mask:0xf bank_mask:0xf bound_ctrl:1
	v_cndmask_b32_e64 v146, v146, v144, s[34:35]
	s_nop 0
	v_mov_b32_dpp v144, v144 row_bcast:15 row_mask:0xa bank_mask:0xf
	v_pk_fma_f32 v[150:151], v[144:145], v[164:165], v[150:151] op_sel_hi:[0,1,1]
	v_mul_f32_e32 v144, v150, v176
	v_mul_f32_e32 v145, v150, v168
	v_fmac_f32_e32 v144, v151, v177
	v_fmac_f32_e32 v145, v151, v169
	v_pk_mul_f32 v[152:153], v[150:151], v[178:179]
	s_nop 0
	v_permlane16_swap_b32_e32 v144, v145
	v_add_f32_e32 v144, v144, v145
	v_pk_fma_f32 v[152:153], v[228:229], v[182:183], v[152:153] op_sel:[1,0,0] op_sel_hi:[1,1,1]
	s_nop 0
	v_add_f32_dpp v144, v144, v144 quad_perm:[1,0,3,2] row_mask:0xf bank_mask:0xf bound_ctrl:1
	ds_read_b128 v[160:163], v19 offset:24576
	ds_read_b128 v[164:167], v19 offset:24592
	v_add_f32_dpp v144, v144, v144 quad_perm:[2,3,0,1] row_mask:0xf bank_mask:0xf bound_ctrl:1
	ds_read_b64 v[168:169], v19 offset:24608
	ds_read2_b32 v[224:225], v232 offset0:0 offset1:16
	v_add_f32_dpp v144, v144, v144 row_half_mirror row_mask:0xf bank_mask:0xf bound_ctrl:1
	s_waitcnt lgkmcnt(7)
	s_nop 0
	v_add_f32_dpp v144, v144, v144 row_mirror row_mask:0xf bank_mask:0xf bound_ctrl:1
	v_cndmask_b32_e64 v146, v146, v144, s[36:37]
	s_nop 0
	v_mov_b32_dpp v144, v144 row_bcast:15 row_mask:0xa bank_mask:0xf
	v_pk_fma_f32 v[152:153], v[144:145], v[180:181], v[152:153] op_sel_hi:[0,1,1]
	v_mul_f32_e32 v144, v152, v192
	v_mul_f32_e32 v145, v152, v184
	v_fmac_f32_e32 v144, v153, v193
	v_fmac_f32_e32 v145, v153, v185
	v_pk_mul_f32 v[150:151], v[152:153], v[194:195]
	s_nop 0
	v_permlane16_swap_b32_e32 v144, v145
	v_add_f32_e32 v144, v144, v145
	v_pk_fma_f32 v[150:151], v[230:231], v[198:199], v[150:151] op_sel:[0,0,0] op_sel_hi:[0,1,1]
	s_nop 0
	v_add_f32_dpp v144, v144, v144 quad_perm:[1,0,3,2] row_mask:0xf bank_mask:0xf bound_ctrl:1
	ds_read_b128 v[176:179], v19 offset:26112
	ds_read_b128 v[180:183], v19 offset:26128
	v_add_f32_dpp v144, v144, v144 quad_perm:[2,3,0,1] row_mask:0xf bank_mask:0xf bound_ctrl:1
	ds_read_b64 v[184:185], v19 offset:26144
	s_nop 0
	v_add_f32_dpp v144, v144, v144 row_half_mirror row_mask:0xf bank_mask:0xf bound_ctrl:1
	s_waitcnt lgkmcnt(7)
; __device__ __forceinline__ void wkv_stage(const WkvT& W, const WkvRaw& raw, size_t rowbase, int h, int q, int c, int tid, const float (&kkc)[4], const float (&kac)[4], const float (&rkc)[4],
;                                           float* sP, float* sV) {
;     const float r[4] = {bflo(raw.r[0]), bfhi(raw.r[0]), bflo(raw.r[1]), bfhi(raw.r[1])}, k[4] = {bflo(raw.k[0]), bfhi(raw.k[0]), bflo(raw.k[1]), bfhi(raw.k[1])};
;     const float a[4] = {bflo(raw.a[0]), bfhi(raw.a[0]), bflo(raw.a[1]), bfhi(raw.a[1])}, l[4] = {bflo(raw.l[0]), bfhi(raw.l[0]), bflo(raw.l[1]), bfhi(raw.l[1])};
;     float kkr[4], km[4], n2 = 0.f, bs = 0.f;
; #pragma unroll
;     for (int e = 0; e < 4; ++e) { kkr[e] = k[e] * kkc[e]; n2 += kkr[e] * kkr[e]; km[e] = k[e] * (1.f + (a[e] - 1.f) * kac[e]); bs += r[e] * km[e] * rkc[e]; }
;     n2 = row16_sum(n2); bs = row16_sum(bs);
;     const float inv = __builtin_amdgcn_rcpf(fmaxf(sqrtf(n2), 1e-12f));
;     const int t = tid >> 4;
;     float* rec = sP + (t * 32 + 2 * (tid & 15)) * 12;
; #pragma unroll
; __device__ __forceinline__ void wkv_phase(const WkvT& W, unsigned char* lds) {
;     ...
;                 for (int t = 0; t < 32; ++t) {
;                     const f32x2 a2 = {nA[0], nA[1]}, w2 = {nA[2], nA[3]}, b2 = {nB[0], nB[1]}, k2 = {nB[2], nB[3]}, r2 = nr; const float v = nv;
;                     if (t + 1 < 32) { nA = *(const f32x4*)(pp + (t + 1) * 384); nB = *(const f32x4*)(pp + (t + 1) * 384 + 4); nr = *(const f32x2*)(pp + (t + 1) * 384 + 8); nv = pv[(t + 1) * 16]; }
;                     float S0 = S.x, S1 = S.y;
;                     float d = S0 * a2.x; d = __builtin_fmaf(S1, a2.y, d);
;                     float t0 = S0 * w2.x; t0 = __builtin_fmaf(v, k2.x, t0); asm volatile("" : "+v"(t0));
;                     float t1 = S1 * w2.y; t1 = __builtin_fmaf(v, k2.y, t1); asm volatile("" : "+v"(t1));
;                     float yprev; const float sa = wkv_reduce(d, ep, yprev);
;                     S0 = __builtin_fmaf(sa, b2.x, t0); asm volatile("" : "+v"(S0));
;                     S1 = __builtin_fmaf(sa, b2.y, t1); asm volatile("" : "+v"(S1));
;                     ep = S0 * r2.x; ep = __builtin_fmaf(S1, r2.y, ep);
;                     S.x = S0; S.y = S1;
;                     if (t >= 1) { const bool hit = oddrow && ((lane & 15) == ((t - 1) & 15)); if (t <= 16) yk0 = hit ? yprev : yk0; else yk1 = hit ? yprev : yk1; }
	s_nop 0
	v_add_f32_dpp v144, v144, v144 row_mirror row_mask:0xf bank_mask:0xf bound_ctrl:1
	v_cndmask_b32_e64 v146, v146, v144, s[38:39]
	s_nop 0
	v_mov_b32_dpp v144, v144 row_bcast:15 row_mask:0xa bank_mask:0xf
	v_pk_fma_f32 v[150:151], v[144:145], v[196:197], v[150:151] op_sel_hi:[0,1,1]
	v_mul_f32_e32 v144, v150, v208
	v_mul_f32_e32 v145, v150, v200
	v_fmac_f32_e32 v144, v151, v209
	v_fmac_f32_e32 v145, v151, v201
	v_pk_mul_f32 v[152:153], v[150:151], v[210:211]
	s_nop 0
	v_permlane16_swap_b32_e32 v144, v145
	v_add_f32_e32 v144, v144, v145
	v_pk_fma_f32 v[152:153], v[230:231], v[214:215], v[152:153] op_sel:[1,0,0] op_sel_hi:[1,1,1]
	s_nop 0
	v_add_f32_dpp v144, v144, v144 quad_perm:[1,0,3,2] row_mask:0xf bank_mask:0xf bound_ctrl:1
	ds_read_b128 v[192:195], v19 offset:27648
	ds_read_b128 v[196:199], v19 offset:27664
	v_add_f32_dpp v144, v144, v144 quad_perm:[2,3,0,1] row_mask:0xf bank_mask:0xf bound_ctrl:1
	ds_read_b64 v[200:201], v19 offset:27680
	ds_read2_b32 v[226:227], v232 offset0:32 offset1:48
	v_add_f32_dpp v144, v144, v144 row_half_mirror row_mask:0xf bank_mask:0xf bound_ctrl:1
	s_waitcnt lgkmcnt(7)
	s_nop 0
	v_add_f32_dpp v144, v144, v144 row_mirror row_mask:0xf bank_mask:0xf bound_ctrl:1
	v_cndmask_b32_e64 v146, v146, v144, s[40:41]
	s_nop 0
	v_mov_b32_dpp v144, v144 row_bcast:15 row_mask:0xa bank_mask:0xf
	v_pk_fma_f32 v[152:153], v[144:145], v[212:213], v[152:153] op_sel_hi:[0,1,1]
	v_mul_f32_e32 v144, v152, v160
	v_mul_f32_e32 v145, v152, v216
	v_fmac_f32_e32 v144, v153, v161
	v_fmac_f32_e32 v145, v153, v217
	v_pk_mul_f32 v[150:151], v[152:153], v[162:163]
	s_nop 0
	v_permlane16_swap_b32_e32 v144, v145
	v_add_f32_e32 v144, v144, v145
	v_pk_fma_f32 v[150:151], v[224:225], v[166:167], v[150:151] op_sel:[0,0,0] op_sel_hi:[0,1,1]
	s_nop 0
	v_add_f32_dpp v144, v144, v144 quad_perm:[1,0,3,2] row_mask:0xf bank_mask:0xf bound_ctrl:1
	ds_read_b128 v[208:211], v19 offset:29184
	ds_read_b128 v[212:215], v19 offset:29200
	v_add_f32_dpp v144, v144, v144 quad_perm:[2,3,0,1] row_mask:0xf bank_mask:0xf bound_ctrl:1
	ds_read_b64 v[216:217], v19 offset:29216
	s_nop 0
	v_add_f32_dpp v144, v144, v144 row_half_mirror row_mask:0xf bank_mask:0xf bound_ctrl:1
	s_waitcnt lgkmcnt(7)
	s_nop 0
	v_add_f32_dpp v144, v144, v144 row_mirror row_mask:0xf bank_mask:0xf bound_ctrl:1
	v_cndmask_b32_e64 v146, v146, v144, s[6:7]
	s_nop 0
	v_mov_b32_dpp v144, v144 row_bcast:15 row_mask:0xa bank_mask:0xf
	v_pk_fma_f32 v[150:151], v[144:145], v[164:165], v[150:151] op_sel_hi:[0,1,1]
	v_mul_f32_e32 v144, v150, v176
	v_mul_f32_e32 v145, v150, v168
	v_fmac_f32_e32 v144, v151, v177
	v_fmac_f32_e32 v145, v151, v169
	v_pk_mul_f32 v[152:153], v[150:151], v[178:179]
	s_nop 0
	v_permlane16_swap_b32_e32 v144, v145
	v_add_f32_e32 v144, v144, v145
	v_pk_fma_f32 v[152:153], v[224:225], v[182:183], v[152:153] op_sel:[1,0,0] op_sel_hi:[1,1,1]
	s_nop 0
	v_add_f32_dpp v144, v144, v144 quad_perm:[1,0,3,2] row_mask:0xf bank_mask:0xf bound_ctrl:1
	ds_read_b128 v[160:163], v19 offset:30720
	ds_read_b128 v[164:167], v19 offset:30736
	v_add_f32_dpp v144, v144, v144 quad_perm:[2,3,0,1] row_mask:0xf bank_mask:0xf bound_ctrl:1
	ds_read_b64 v[168:169], v19 offset:30752
	ds_read2_b32 v[228:229], v232 offset0:64 offset1:80
	v_add_f32_dpp v144, v144, v144 row_half_mirror row_mask:0xf bank_mask:0xf bound_ctrl:1
	s_waitcnt lgkmcnt(7)
	s_nop 0
	v_add_f32_dpp v144, v144, v144 row_mirror row_mask:0xf bank_mask:0xf bound_ctrl:1
	v_cndmask_b32_e64 v147, v147, v144, s[10:11]
	s_nop 0
	v_mov_b32_dpp v144, v144 row_bcast:15 row_mask:0xa bank_mask:0xf
	v_pk_fma_f32 v[152:153], v[144:145], v[180:181], v[152:153] op_sel_hi:[0,1,1]
	v_mul_f32_e32 v144, v152, v192
	v_mul_f32_e32 v145, v152, v184
	v_fmac_f32_e32 v144, v153, v193
	v_fmac_f32_e32 v145, v153, v185
	v_pk_mul_f32 v[150:151], v[152:153], v[194:195]
	s_nop 0
	v_permlane16_swap_b32_e32 v144, v145
	v_add_f32_e32 v144, v144, v145
	v_pk_fma_f32 v[150:151], v[226:227], v[198:199], v[150:151] op_sel:[0,0,0] op_sel_hi:[0,1,1]
	s_nop 0
	v_add_f32_dpp v144, v144, v144 quad_perm:[1,0,3,2] row_mask:0xf bank_mask:0xf bound_ctrl:1
	ds_read_b128 v[176:179], v19 offset:32256
	ds_read_b128 v[180:183], v19 offset:32272
	v_add_f32_dpp v144, v144, v144 quad_perm:[2,3,0,1] row_mask:0xf bank_mask:0xf bound_ctrl:1
	ds_read_b64 v[184:185], v19 offset:32288
	s_nop 0
	v_add_f32_dpp v144, v144, v144 row_half_mirror row_mask:0xf bank_mask:0xf bound_ctrl:1
	s_waitcnt lgkmcnt(7)
	s_nop 0
	v_add_f32_dpp v144, v144, v144 row_mirror row_mask:0xf bank_mask:0xf bound_ctrl:1
	v_cndmask_b32_e64 v147, v147, v144, s[12:13]
	s_nop 0
	v_mov_b32_dpp v144, v144 row_bcast:15 row_mask:0xa bank_mask:0xf
	v_pk_fma_f32 v[150:151], v[144:145], v[196:197], v[150:151] op_sel_hi:[0,1,1]
	v_mul_f32_e32 v144, v150, v208
	v_mul_f32_e32 v145, v150, v200
	v_fmac_f32_e32 v144, v151, v209
	v_fmac_f32_e32 v145, v151, v201
	v_pk_mul_f32 v[152:153], v[150:151], v[210:211]
	s_nop 0
	v_permlane16_swap_b32_e32 v144, v145
	v_add_f32_e32 v144, v144, v145
	v_pk_fma_f32 v[152:153], v[226:227], v[214:215], v[152:153] op_sel:[1,0,0] op_sel_hi:[1,1,1]
	s_nop 0
	v_add_f32_dpp v144, v144, v144 quad_perm:[1,0,3,2] row_mask:0xf bank_mask:0xf bound_ctrl:1
	ds_read_b128 v[192:195], v19 offset:33792
	ds_read_b128 v[196:199], v19 offset:33808
	v_add_f32_dpp v144, v144, v144 quad_perm:[2,3,0,1] row_mask:0xf bank_mask:0xf bound_ctrl:1
	ds_read_b64 v[200:201], v19 offset:33824
	ds_read2_b32 v[230:231], v232 offset0:96 offset1:112
	v_add_f32_dpp v144, v144, v144 row_half_mirror row_mask:0xf bank_mask:0xf bound_ctrl:1
	s_waitcnt lgkmcnt(7)
; __device__ __forceinline__ void wkv_stage(const WkvT& W, const WkvRaw& raw, size_t rowbase, int h, int q, int c, int tid, const float (&kkc)[4], const float (&kac)[4], const float (&rkc)[4],
;                                           float* sP, float* sV) {
;     const float r[4] = {bflo(raw.r[0]), bfhi(raw.r[0]), bflo(raw.r[1]), bfhi(raw.r[1])}, k[4] = {bflo(raw.k[0]), bfhi(raw.k[0]), bflo(raw.k[1]), bfhi(raw.k[1])};
;     const float a[4] = {bflo(raw.a[0]), bfhi(raw.a[0]), bflo(raw.a[1]), bfhi(raw.a[1])}, l[4] = {bflo(raw.l[0]), bfhi(raw.l[0]), bflo(raw.l[1]), bfhi(raw.l[1])};
;     float kkr[4], km[4], n2 = 0.f, bs = 0.f;
; #pragma unroll
;     for (int e = 0; e < 4; ++e) { kkr[e] = k[e] * kkc[e]; n2 += kkr[e] * kkr[e]; km[e] = k[e] * (1.f + (a[e] - 1.f) * kac[e]); bs += r[e] * km[e] * rkc[e]; }
;     n2 = row16_sum(n2); bs = row16_sum(bs);
;     const float inv = __builtin_amdgcn_rcpf(fmaxf(sqrtf(n2), 1e-12f));
;     const int t = tid >> 4;
;     float* rec = sP + (t * 32 + 2 * (tid & 15)) * 12;
; #pragma unroll
; __device__ __forceinline__ void wkv_phase(const WkvT& W, unsigned char* lds) {
;     ...
;                 for (int t = 0; t < 32; ++t) {
;                     const f32x2 a2 = {nA[0], nA[1]}, w2 = {nA[2], nA[3]}, b2 = {nB[0], nB[1]}, k2 = {nB[2], nB[3]}, r2 = nr; const float v = nv;
;                     if (t + 1 < 32) { nA = *(const f32x4*)(pp + (t + 1) * 384); nB = *(const f32x4*)(pp + (t + 1) * 384 + 4); nr = *(const f32x2*)(pp + (t + 1) * 384 + 8); nv = pv[(t + 1) * 16]; }
;                     float S0 = S.x, S1 = S.y;
;                     float d = S0 * a2.x; d = __builtin_fmaf(S1, a2.y, d);
;                     float t0 = S0 * w2.x; t0 = __builtin_fmaf(v, k2.x, t0); asm volatile("" : "+v"(t0));
;                     float t1 = S1 * w2.y; t1 = __builtin_fmaf(v, k2.y, t1); asm volatile("" : "+v"(t1));
;                     float yprev; const float sa = wkv_reduce(d, ep, yprev);
;                     S0 = __builtin_fmaf(sa, b2.x, t0); asm volatile("" : "+v"(S0));
;                     S1 = __builtin_fmaf(sa, b2.y, t1); asm volatile("" : "+v"(S1));
;                     ep = S0 * r2.x; ep = __builtin_fmaf(S1, r2.y, ep);
;                     S.x = S0; S.y = S1;
;                     if (t >= 1) { const bool hit = oddrow && ((lane & 15) == ((t - 1) & 15)); if (t <= 16) yk0 = hit ? yprev : yk0; else yk1 = hit ? yprev : yk1; }
	s_nop 0
	v_add_f32_dpp v144, v144, v144 row_mirror row_mask:0xf bank_mask:0xf bound_ctrl:1
	v_cndmask_b32_e64 v147, v147, v144, s[14:15]
	s_nop 0
	v_mov_b32_dpp v144, v144 row_bcast:15 row_mask:0xa bank_mask:0xf
	v_pk_fma_f32 v[152:153], v[144:145], v[212:213], v[152:153] op_sel_hi:[0,1,1]
	v_mul_f32_e32 v144, v152, v160
	v_mul_f32_e32 v145, v152, v216
	v_fmac_f32_e32 v144, v153, v161
	v_fmac_f32_e32 v145, v153, v217
	v_pk_mul_f32 v[150:151], v[152:153], v[162:163]
	s_nop 0
	v_permlane16_swap_b32_e32 v144, v145
	v_add_f32_e32 v144, v144, v145
	v_pk_fma_f32 v[150:151], v[228:229], v[166:167], v[150:151] op_sel:[0,0,0] op_sel_hi:[0,1,1]
	s_nop 0
	v_add_f32_dpp v144, v144, v144 quad_perm:[1,0,3,2] row_mask:0xf bank_mask:0xf bound_ctrl:1
	ds_read_b128 v[208:211], v19 offset:35328
	ds_read_b128 v[212:215], v19 offset:35344
	v_add_f32_dpp v144, v144, v144 quad_perm:[2,3,0,1] row_mask:0xf bank_mask:0xf bound_ctrl:1
	ds_read_b64 v[216:217], v19 offset:35360
	s_nop 0
	v_add_f32_dpp v144, v144, v144 row_half_mirror row_mask:0xf bank_mask:0xf bound_ctrl:1
	s_waitcnt lgkmcnt(7)
	s_nop 0
	v_add_f32_dpp v144, v144, v144 row_mirror row_mask:0xf bank_mask:0xf bound_ctrl:1
	v_cndmask_b32_e64 v147, v147, v144, s[16:17]
	s_nop 0
	v_mov_b32_dpp v144, v144 row_bcast:15 row_mask:0xa bank_mask:0xf
	v_pk_fma_f32 v[150:151], v[144:145], v[164:165], v[150:151] op_sel_hi:[0,1,1]
	v_mul_f32_e32 v144, v150, v176
	v_mul_f32_e32 v145, v150, v168
	v_fmac_f32_e32 v144, v151, v177
	v_fmac_f32_e32 v145, v151, v169
	v_pk_mul_f32 v[152:153], v[150:151], v[178:179]
	s_nop 0
	v_permlane16_swap_b32_e32 v144, v145
	v_add_f32_e32 v144, v144, v145
	v_pk_fma_f32 v[152:153], v[228:229], v[182:183], v[152:153] op_sel:[1,0,0] op_sel_hi:[1,1,1]
	s_nop 0
	v_add_f32_dpp v144, v144, v144 quad_perm:[1,0,3,2] row_mask:0xf bank_mask:0xf bound_ctrl:1
	ds_read_b128 v[160:163], v19 offset:36864
	ds_read_b128 v[164:167], v19 offset:36880
	v_add_f32_dpp v144, v144, v144 quad_perm:[2,3,0,1] row_mask:0xf bank_mask:0xf bound_ctrl:1
	ds_read_b64 v[168:169], v19 offset:36896
	ds_read2_b32 v[224:225], v232 offset0:128 offset1:144
	v_add_f32_dpp v144, v144, v144 row_half_mirror row_mask:0xf bank_mask:0xf bound_ctrl:1
	s_waitcnt lgkmcnt(7)
	s_nop 0
	v_add_f32_dpp v144, v144, v144 row_mirror row_mask:0xf bank_mask:0xf bound_ctrl:1
	v_cndmask_b32_e64 v147, v147, v144, s[18:19]
	s_nop 0
	v_mov_b32_dpp v144, v144 row_bcast:15 row_mask:0xa bank_mask:0xf
	v_pk_fma_f32 v[152:153], v[144:145], v[180:181], v[152:153] op_sel_hi:[0,1,1]
	v_mul_f32_e32 v144, v152, v192
	v_mul_f32_e32 v145, v152, v184
	v_fmac_f32_e32 v144, v153, v193
	v_fmac_f32_e32 v145, v153, v185
	v_pk_mul_f32 v[150:151], v[152:153], v[194:195]
	s_nop 0
	v_permlane16_swap_b32_e32 v144, v145
	v_add_f32_e32 v144, v144, v145
	v_pk_fma_f32 v[150:151], v[230:231], v[198:199], v[150:151] op_sel:[0,0,0] op_sel_hi:[0,1,1]
	s_nop 0
	v_add_f32_dpp v144, v144, v144 quad_perm:[1,0,3,2] row_mask:0xf bank_mask:0xf bound_ctrl:1
	ds_read_b128 v[176:179], v19 offset:38400
	ds_read_b128 v[180:183], v19 offset:38416
	v_add_f32_dpp v144, v144, v144 quad_perm:[2,3,0,1] row_mask:0xf bank_mask:0xf bound_ctrl:1
	ds_read_b64 v[184:185], v19 offset:38432
	s_nop 0
	v_add_f32_dpp v144, v144, v144 row_half_mirror row_mask:0xf bank_mask:0xf bound_ctrl:1
	s_waitcnt lgkmcnt(7)
	s_nop 0
	v_add_f32_dpp v144, v144, v144 row_mirror row_mask:0xf bank_mask:0xf bound_ctrl:1
	v_cndmask_b32_e64 v147, v147, v144, s[20:21]
	s_nop 0
	v_mov_b32_dpp v144, v144 row_bcast:15 row_mask:0xa bank_mask:0xf
	v_pk_fma_f32 v[150:151], v[144:145], v[196:197], v[150:151] op_sel_hi:[0,1,1]
	v_mul_f32_e32 v144, v150, v208
	v_mul_f32_e32 v145, v150, v200
	v_fmac_f32_e32 v144, v151, v209
	v_fmac_f32_e32 v145, v151, v201
	v_pk_mul_f32 v[152:153], v[150:151], v[210:211]
	s_nop 0
	v_permlane16_swap_b32_e32 v144, v145
	v_add_f32_e32 v144, v144, v145
	v_pk_fma_f32 v[152:153], v[230:231], v[214:215], v[152:153] op_sel:[1,0,0] op_sel_hi:[1,1,1]
	s_nop 0
	v_add_f32_dpp v144, v144, v144 quad_perm:[1,0,3,2] row_mask:0xf bank_mask:0xf bound_ctrl:1
	ds_read_b128 v[192:195], v19 offset:39936
	ds_read_b128 v[196:199], v19 offset:39952
	v_add_f32_dpp v144, v144, v144 quad_perm:[2,3,0,1] row_mask:0xf bank_mask:0xf bound_ctrl:1
	ds_read_b64 v[200:201], v19 offset:39968
	ds_read2_b32 v[226:227], v232 offset0:160 offset1:176
	v_add_f32_dpp v144, v144, v144 row_half_mirror row_mask:0xf bank_mask:0xf bound_ctrl:1
	s_waitcnt lgkmcnt(7)
	s_nop 0
	v_add_f32_dpp v144, v144, v144 row_mirror row_mask:0xf bank_mask:0xf bound_ctrl:1
	v_cndmask_b32_e64 v147, v147, v144, s[22:23]
	s_nop 0
	v_mov_b32_dpp v144, v144 row_bcast:15 row_mask:0xa bank_mask:0xf
	v_pk_fma_f32 v[152:153], v[144:145], v[212:213], v[152:153] op_sel_hi:[0,1,1]
	v_mul_f32_e32 v144, v152, v160
	v_mul_f32_e32 v145, v152, v216
	v_fmac_f32_e32 v144, v153, v161
	v_fmac_f32_e32 v145, v153, v217
	v_pk_mul_f32 v[150:151], v[152:153], v[162:163]
	s_nop 0
	v_permlane16_swap_b32_e32 v144, v145
	v_add_f32_e32 v144, v144, v145
	v_pk_fma_f32 v[150:151], v[224:225], v[166:167], v[150:151] op_sel:[0,0,0] op_sel_hi:[0,1,1]
	s_nop 0
	v_add_f32_dpp v144, v144, v144 quad_perm:[1,0,3,2] row_mask:0xf bank_mask:0xf bound_ctrl:1
	ds_read_b128 v[208:211], v19 offset:41472
	ds_read_b128 v[212:215], v19 offset:41488
	v_add_f32_dpp v144, v144, v144 quad_perm:[2,3,0,1] row_mask:0xf bank_mask:0xf bound_ctrl:1
	ds_read_b64 v[216:217], v19 offset:41504
	s_nop 0
	v_add_f32_dpp v144, v144, v144 row_half_mirror row_mask:0xf bank_mask:0xf bound_ctrl:1
	s_waitcnt lgkmcnt(7)
; __device__ __forceinline__ float wkv_reduce(float x, float y, float& zy) {
;     auto f = __builtin_amdgcn_permlane16_swap(__float_as_uint(x), __float_as_uint(y), false, false);
;     float z = __uint_as_float(f[0]) + __uint_as_float(f[1]);
;     z += dpp_f(z, 0); z += dpp_f(z, 1); z += dpp_f(z, 2); z += dpp_f(z, 3);
;     zy = z;
;     const int zi = __builtin_bit_cast(int, z);
;     return __builtin_bit_cast(float, __builtin_amdgcn_update_dpp(zi, zi, 0x142, 0xA, 0xF, false));
; }
; __device__ __forceinline__ void wkv_phase(const WkvT& W, unsigned char* lds) {
;     ...
;                 for (int t = 0; t < 32; ++t) {
;                     const f32x2 a2 = {nA[0], nA[1]}, w2 = {nA[2], nA[3]}, b2 = {nB[0], nB[1]}, k2 = {nB[2], nB[3]}, r2 = nr; const float v = nv;
;                     if (t + 1 < 32) { nA = *(const f32x4*)(pp + (t + 1) * 384); nB = *(const f32x4*)(pp + (t + 1) * 384 + 4); nr = *(const f32x2*)(pp + (t + 1) * 384 + 8); nv = pv[(t + 1) * 16]; }
;                     float S0 = S.x, S1 = S.y;
;                     float d = S0 * a2.x; d = __builtin_fmaf(S1, a2.y, d);
;                     float t0 = S0 * w2.x; t0 = __builtin_fmaf(v, k2.x, t0); asm volatile("" : "+v"(t0));
;                     float t1 = S1 * w2.y; t1 = __builtin_fmaf(v, k2.y, t1); asm volatile("" : "+v"(t1));
;                     float yprev; const float sa = wkv_reduce(d, ep, yprev);
;                     S0 = __builtin_fmaf(sa, b2.x, t0); asm volatile("" : "+v"(S0));
;                     S1 = __builtin_fmaf(sa, b2.y, t1); asm volatile("" : "+v"(S1));
;                     ep = S0 * r2.x; ep = __builtin_fmaf(S1, r2.y, ep);
;                     S.x = S0; S.y = S1;
;                     if (t >= 1) { const bool hit = oddrow && ((lane & 15) == ((t - 1) & 15)); if (t <= 16) yk0 = hit ? yprev : yk0; else yk1 = hit ? yprev : yk1; }
	s_nop 0
	v_add_f32_dpp v144, v144, v144 row_mirror row_mask:0xf bank_mask:0xf bound_ctrl:1
	v_cndmask_b32_e64 v147, v147, v144, s[24:25]
	s_nop 0
	v_mov_b32_dpp v144, v144 row_bcast:15 row_mask:0xa bank_mask:0xf
	v_pk_fma_f32 v[150:151], v[144:145], v[164:165], v[150:151] op_sel_hi:[0,1,1]
	v_mul_f32_e32 v144, v150, v176
	v_mul_f32_e32 v145, v150, v168
	v_fmac_f32_e32 v144, v151, v177
	v_fmac_f32_e32 v145, v151, v169
	v_pk_mul_f32 v[152:153], v[150:151], v[178:179]
	s_nop 0
	v_permlane16_swap_b32_e32 v144, v145
	v_add_f32_e32 v144, v144, v145
	v_pk_fma_f32 v[152:153], v[224:225], v[182:183], v[152:153] op_sel:[1,0,0] op_sel_hi:[1,1,1]
	s_nop 0
	v_add_f32_dpp v144, v144, v144 quad_perm:[1,0,3,2] row_mask:0xf bank_mask:0xf bound_ctrl:1
	ds_read_b128 v[160:163], v19 offset:43008
	ds_read_b128 v[164:167], v19 offset:43024
	v_add_f32_dpp v144, v144, v144 quad_perm:[2,3,0,1] row_mask:0xf bank_mask:0xf bound_ctrl:1
	ds_read_b64 v[168:169], v19 offset:43040
	ds_read2_b32 v[228:229], v232 offset0:192 offset1:208
	v_add_f32_dpp v144, v144, v144 row_half_mirror row_mask:0xf bank_mask:0xf bound_ctrl:1
	s_waitcnt lgkmcnt(7)
	s_nop 0
	v_add_f32_dpp v144, v144, v144 row_mirror row_mask:0xf bank_mask:0xf bound_ctrl:1
	v_cndmask_b32_e64 v147, v147, v144, s[26:27]
	s_nop 0
	v_mov_b32_dpp v144, v144 row_bcast:15 row_mask:0xa bank_mask:0xf
	v_pk_fma_f32 v[152:153], v[144:145], v[180:181], v[152:153] op_sel_hi:[0,1,1]
	v_mul_f32_e32 v144, v152, v192
	v_mul_f32_e32 v145, v152, v184
	v_fmac_f32_e32 v144, v153, v193
	v_fmac_f32_e32 v145, v153, v185
	v_pk_mul_f32 v[150:151], v[152:153], v[194:195]
	s_nop 0
	v_permlane16_swap_b32_e32 v144, v145
	v_add_f32_e32 v144, v144, v145
	v_pk_fma_f32 v[150:151], v[226:227], v[198:199], v[150:151] op_sel:[0,0,0] op_sel_hi:[0,1,1]
	s_nop 0
	v_add_f32_dpp v144, v144, v144 quad_perm:[1,0,3,2] row_mask:0xf bank_mask:0xf bound_ctrl:1
	ds_read_b128 v[176:179], v19 offset:44544
	ds_read_b128 v[180:183], v19 offset:44560
	v_add_f32_dpp v144, v144, v144 quad_perm:[2,3,0,1] row_mask:0xf bank_mask:0xf bound_ctrl:1
	ds_read_b64 v[184:185], v19 offset:44576
	s_nop 0
	v_add_f32_dpp v144, v144, v144 row_half_mirror row_mask:0xf bank_mask:0xf bound_ctrl:1
	s_waitcnt lgkmcnt(7)
	s_nop 0
	v_add_f32_dpp v144, v144, v144 row_mirror row_mask:0xf bank_mask:0xf bound_ctrl:1
	v_cndmask_b32_e64 v147, v147, v144, s[28:29]
	s_nop 0
	v_mov_b32_dpp v144, v144 row_bcast:15 row_mask:0xa bank_mask:0xf
	v_pk_fma_f32 v[150:151], v[144:145], v[196:197], v[150:151] op_sel_hi:[0,1,1]
	v_mul_f32_e32 v144, v150, v208
	v_mul_f32_e32 v145, v150, v200
	v_fmac_f32_e32 v144, v151, v209
	v_fmac_f32_e32 v145, v151, v201
	v_pk_mul_f32 v[152:153], v[150:151], v[210:211]
	s_nop 0
	v_permlane16_swap_b32_e32 v144, v145
	v_add_f32_e32 v144, v144, v145
	v_pk_fma_f32 v[152:153], v[226:227], v[214:215], v[152:153] op_sel:[1,0,0] op_sel_hi:[1,1,1]
	s_nop 0
	v_add_f32_dpp v144, v144, v144 quad_perm:[1,0,3,2] row_mask:0xf bank_mask:0xf bound_ctrl:1
	ds_read_b128 v[192:195], v19 offset:46080
	ds_read_b128 v[196:199], v19 offset:46096
	v_add_f32_dpp v144, v144, v144 quad_perm:[2,3,0,1] row_mask:0xf bank_mask:0xf bound_ctrl:1
	ds_read_b64 v[200:201], v19 offset:46112
	ds_read2_b32 v[230:231], v232 offset0:224 offset1:240
	v_add_f32_dpp v144, v144, v144 row_half_mirror row_mask:0xf bank_mask:0xf bound_ctrl:1
	s_waitcnt lgkmcnt(7)
	s_nop 0
	v_add_f32_dpp v144, v144, v144 row_mirror row_mask:0xf bank_mask:0xf bound_ctrl:1
	v_cndmask_b32_e64 v147, v147, v144, s[30:31]
	s_nop 0
	v_mov_b32_dpp v144, v144 row_bcast:15 row_mask:0xa bank_mask:0xf
	v_pk_fma_f32 v[152:153], v[144:145], v[212:213], v[152:153] op_sel_hi:[0,1,1]
	v_mul_f32_e32 v144, v152, v160
	v_mul_f32_e32 v145, v152, v216
	v_fmac_f32_e32 v144, v153, v161
	v_fmac_f32_e32 v145, v153, v217
	v_pk_mul_f32 v[150:151], v[152:153], v[162:163]
	s_nop 0
	v_permlane16_swap_b32_e32 v144, v145
	v_add_f32_e32 v144, v144, v145
	v_pk_fma_f32 v[150:151], v[228:229], v[166:167], v[150:151] op_sel:[0,0,0] op_sel_hi:[0,1,1]
	s_nop 0
	v_add_f32_dpp v144, v144, v144 quad_perm:[1,0,3,2] row_mask:0xf bank_mask:0xf bound_ctrl:1
	ds_read_b128 v[208:211], v19 offset:47616
	ds_read_b128 v[212:215], v19 offset:47632
	v_add_f32_dpp v144, v144, v144 quad_perm:[2,3,0,1] row_mask:0xf bank_mask:0xf bound_ctrl:1
	ds_read_b64 v[216:217], v19 offset:47648
	s_nop 0
	v_add_f32_dpp v144, v144, v144 row_half_mirror row_mask:0xf bank_mask:0xf bound_ctrl:1
	s_waitcnt lgkmcnt(7)
	s_nop 0
	v_add_f32_dpp v144, v144, v144 row_mirror row_mask:0xf bank_mask:0xf bound_ctrl:1
	v_cndmask_b32_e64 v147, v147, v144, s[34:35]
	s_nop 0
	v_mov_b32_dpp v144, v144 row_bcast:15 row_mask:0xa bank_mask:0xf
	v_pk_fma_f32 v[150:151], v[144:145], v[164:165], v[150:151] op_sel_hi:[0,1,1]
	v_mul_f32_e32 v144, v150, v176
	v_mul_f32_e32 v145, v150, v168
	v_fmac_f32_e32 v144, v151, v177
	v_fmac_f32_e32 v145, v151, v169
	v_pk_mul_f32 v[152:153], v[150:151], v[178:179]
	s_nop 0
	v_permlane16_swap_b32_e32 v144, v145
	v_add_f32_e32 v144, v144, v145
	v_pk_fma_f32 v[152:153], v[228:229], v[182:183], v[152:153] op_sel:[1,0,0] op_sel_hi:[1,1,1]
	s_nop 0
	v_add_f32_dpp v144, v144, v144 quad_perm:[1,0,3,2] row_mask:0xf bank_mask:0xf bound_ctrl:1
	s_nop 1
	v_add_f32_dpp v144, v144, v144 quad_perm:[2,3,0,1] row_mask:0xf bank_mask:0xf bound_ctrl:1
	s_nop 1
	v_add_f32_dpp v144, v144, v144 row_half_mirror row_mask:0xf bank_mask:0xf bound_ctrl:1
	s_waitcnt lgkmcnt(3)
; __device__ __forceinline__ void wkv_phase(const WkvT& W, unsigned char* lds) {
;     ...
;                 for (int t = 0; t < 32; ++t) {
;                     const f32x2 a2 = {nA[0], nA[1]}, w2 = {nA[2], nA[3]}, b2 = {nB[0], nB[1]}, k2 = {nB[2], nB[3]}, r2 = nr; const float v = nv;
;                     if (t + 1 < 32) { nA = *(const f32x4*)(pp + (t + 1) * 384); nB = *(const f32x4*)(pp + (t + 1) * 384 + 4); nr = *(const f32x2*)(pp + (t + 1) * 384 + 8); nv = pv[(t + 1) * 16]; }
;                     float S0 = S.x, S1 = S.y;
;                     float d = S0 * a2.x; d = __builtin_fmaf(S1, a2.y, d);
;                     float t0 = S0 * w2.x; t0 = __builtin_fmaf(v, k2.x, t0); asm volatile("" : "+v"(t0));
;                     float t1 = S1 * w2.y; t1 = __builtin_fmaf(v, k2.y, t1); asm volatile("" : "+v"(t1));
;                     float yprev; const float sa = wkv_reduce(d, ep, yprev);
;                     S0 = __builtin_fmaf(sa, b2.x, t0); asm volatile("" : "+v"(S0));
;                     S1 = __builtin_fmaf(sa, b2.y, t1); asm volatile("" : "+v"(S1));
;                     ep = S0 * r2.x; ep = __builtin_fmaf(S1, r2.y, ep);
;                     S.x = S0; S.y = S1;
;                     if (t >= 1) { const bool hit = oddrow && ((lane & 15) == ((t - 1) & 15)); if (t <= 16) yk0 = hit ? yprev : yk0; else yk1 = hit ? yprev : yk1; }
;                 }
;                 { float ylast; (void)wkv_reduce(0.f, ep, ylast); yk1 = (oddrow && (lane & 15) == 15) ? ylast : yk1; }
;                 if (oddrow) { sY[bi * 512 + (lane & 15) * 16 + il] = yk0; sY[bi * 512 + (16 + (lane & 15)) * 16 + il] = yk1; }
	s_nop 0
	v_add_f32_dpp v144, v144, v144 row_mirror row_mask:0xf bank_mask:0xf bound_ctrl:1
	v_cndmask_b32_e64 v147, v147, v144, s[36:37]
	s_nop 0
	v_mov_b32_dpp v144, v144 row_bcast:15 row_mask:0xa bank_mask:0xf
	v_pk_fma_f32 v[152:153], v[144:145], v[180:181], v[152:153] op_sel_hi:[0,1,1]
	v_mul_f32_e32 v144, v152, v192
	v_mul_f32_e32 v145, v152, v184
	v_fmac_f32_e32 v144, v153, v193
	v_fmac_f32_e32 v145, v153, v185
	v_pk_mul_f32 v[150:151], v[152:153], v[194:195]
	s_nop 0
	v_permlane16_swap_b32_e32 v144, v145
	v_add_f32_e32 v144, v144, v145
	v_pk_fma_f32 v[150:151], v[230:231], v[198:199], v[150:151] op_sel:[0,0,0] op_sel_hi:[0,1,1]
	s_nop 0
	v_add_f32_dpp v144, v144, v144 quad_perm:[1,0,3,2] row_mask:0xf bank_mask:0xf bound_ctrl:1
	s_nop 1
	v_add_f32_dpp v144, v144, v144 quad_perm:[2,3,0,1] row_mask:0xf bank_mask:0xf bound_ctrl:1
	s_nop 1
	v_add_f32_dpp v144, v144, v144 row_half_mirror row_mask:0xf bank_mask:0xf bound_ctrl:1
	s_waitcnt lgkmcnt(0)
	s_nop 0
	v_add_f32_dpp v144, v144, v144 row_mirror row_mask:0xf bank_mask:0xf bound_ctrl:1
	v_cndmask_b32_e64 v147, v147, v144, s[38:39]
	s_nop 0
	v_mov_b32_dpp v144, v144 row_bcast:15 row_mask:0xa bank_mask:0xf
	v_pk_fma_f32 v[150:151], v[144:145], v[196:197], v[150:151] op_sel_hi:[0,1,1]
	v_mul_f32_e32 v144, v150, v208
	v_mul_f32_e32 v145, v150, v200
	v_fmac_f32_e32 v144, v151, v209
	v_fmac_f32_e32 v145, v151, v201
	v_pk_mul_f32 v[142:143], v[150:151], v[210:211]
	s_nop 0
	v_permlane16_swap_b32_e32 v144, v145
	v_add_f32_e32 v144, v144, v145
	v_pk_fma_f32 v[142:143], v[230:231], v[214:215], v[142:143] op_sel:[1,0,0] op_sel_hi:[1,1,1]
	s_nop 0
	v_add_f32_dpp v144, v144, v144 quad_perm:[1,0,3,2] row_mask:0xf bank_mask:0xf bound_ctrl:1
	s_nop 1
	v_add_f32_dpp v144, v144, v144 quad_perm:[2,3,0,1] row_mask:0xf bank_mask:0xf bound_ctrl:1
	s_nop 1
	v_add_f32_dpp v144, v144, v144 row_half_mirror row_mask:0xf bank_mask:0xf bound_ctrl:1
	s_nop 1
	v_add_f32_dpp v144, v144, v144 row_mirror row_mask:0xf bank_mask:0xf bound_ctrl:1
	v_cndmask_b32_e64 v147, v147, v144, s[40:41]
	s_nop 0
	v_mov_b32_dpp v144, v144 row_bcast:15 row_mask:0xa bank_mask:0xf
	v_pk_fma_f32 v[142:143], v[144:145], v[212:213], v[142:143] op_sel_hi:[0,1,1]
	v_mul_f32_e32 v145, v142, v216
	v_fmac_f32_e32 v145, v143, v217
	s_nop 1
	v_permlane16_swap_b32_e32 v148, v145
	v_add_f32_e32 v145, v148, v145
	s_nop 1
	v_add_f32_dpp v145, v145, v145 quad_perm:[1,0,3,2] row_mask:0xf bank_mask:0xf bound_ctrl:1
	s_nop 1
	v_add_f32_dpp v145, v145, v145 quad_perm:[2,3,0,1] row_mask:0xf bank_mask:0xf bound_ctrl:1
	s_nop 1
	v_add_f32_dpp v145, v145, v145 row_half_mirror row_mask:0xf bank_mask:0xf bound_ctrl:1
	s_nop 1
	v_add_f32_dpp v145, v145, v145 row_mirror row_mask:0xf bank_mask:0xf bound_ctrl:1
	v_cndmask_b32_e64 v147, v147, v145, s[6:7]
	s_and_saveexec_b64 s[46:47], s[4:5]
	ds_write2st64_b32 v29, v146, v147 offset1:4
; __device__ __forceinline__ void wkv_stage(const WkvT& W, const WkvRaw& raw, size_t rowbase, int h, int q, int c, int tid, const float (&kkc)[4], const float (&kac)[4], const float (&rkc)[4],
;                                           float* sP, float* sV) {
;     const float r[4] = {bflo(raw.r[0]), bfhi(raw.r[0]), bflo(raw.r[1]), bfhi(raw.r[1])}, k[4] = {bflo(raw.k[0]), bfhi(raw.k[0]), bflo(raw.k[1]), bfhi(raw.k[1])};
;     const float a[4] = {bflo(raw.a[0]), bfhi(raw.a[0]), bflo(raw.a[1]), bfhi(raw.a[1])}, l[4] = {bflo(raw.l[0]), bfhi(raw.l[0]), bflo(raw.l[1]), bfhi(raw.l[1])};
;     float kkr[4], km[4], n2 = 0.f, bs = 0.f;
; #pragma unroll
;     for (int e = 0; e < 4; ++e) { kkr[e] = k[e] * kkc[e]; n2 += kkr[e] * kkr[e]; km[e] = k[e] * (1.f + (a[e] - 1.f) * kac[e]); bs += r[e] * km[e] * rkc[e]; }
;     n2 = row16_sum(n2); bs = row16_sum(bs);
;     const float inv = __builtin_amdgcn_rcpf(fmaxf(sqrtf(n2), 1e-12f));
;     const int t = tid >> 4;
;     float* rec = sP + (t * 32 + 2 * (tid & 15)) * 12;
; #pragma unroll
;     for (int hlf = 0; hlf < 2; ++hlf) { const int e = 2 * hlf; float* rp = rec + hlf * 12;
;         *(f32x4*)(rp) = (f32x4){-kkr[e] * inv, -kkr[e + 1] * inv, __builtin_amdgcn_exp2f(LOG2E_ * l[e]), __builtin_amdgcn_exp2f(LOG2E_ * l[e + 1])};
;         *(f32x4*)(rp + 4) = (f32x4){kkr[e] * inv * a[e], kkr[e + 1] * inv * a[e + 1], km[e], km[e + 1]};
;         *(f32x2*)(rp + 8) = (f32x2){r[e], r[e + 1]}; }
;     if ((tid & 15) < 4) *(f32x4*)(sV + t * 16 + 4 * (tid & 15)) = (f32x4){bflo(raw.v[0]), bfhi(raw.v[0]), bflo(raw.v[1]), bfhi(raw.v[1])};
;     if (q == 0 && (tid & 15) == 0) W.bonus[(rowbase + (size_t)c * 32 + t) * 32 + h] = bs;
; __device__ __forceinline__ void wkv_phase(const WkvT& W, unsigned char* lds) {
;     ...
;             if (c + 1 < 256) wkv_stage(W, raw, rowbase, h, q, c + 1, tid, kkc, kac, rkc, sP + bn, sV + (bi ^ 1) * 512);
;             lds_barrier();
;             {
;                 const int t = tid >> 4, i = tid & 15; const float yv = sY[bi * 512 + t * 16 + i];
;                 const size_t row = rowbase + (size_t)c * 32 + t;
;                 W.Y[row * DM + cbase + q * 16 + i] = f2bf(yv);
;                 const float s1 = row16_sum(yv), s2 = row16_sum(yv * yv);
;                 if (i == 0) *(f32x2*)(W.stats + ((row * 32 + h) * 4 + q) * 2) = (f32x2){s1, s2};
;             }
.LBB0_1626:
	s_or_b64 exec, exec, s[46:47]
	s_waitcnt vmcnt(2)
	v_lshlrev_b32_e32 v126, 16, v52
	v_and_b32_e32 v127, 0xffff0000, v52
	v_and_b32_e32 v135, 0xffff0000, v53
	v_lshlrev_b32_e32 v134, 16, v53
	v_pk_mul_f32 v[128:129], v[6:7], v[126:127]
	v_pk_mul_f32 v[136:137], v[8:9], v[134:135]
	v_pk_mul_f32 v[58:59], v[128:129], v[128:129]
	v_pk_mul_f32 v[56:57], v[136:137], v[136:137]
	v_add_f32_e32 v16, v58, v59
	v_add_f32_e32 v16, v56, v16
	v_add_f32_e32 v16, v57, v16
	s_waitcnt vmcnt(0)
	v_lshlrev_b32_e32 v57, 16, v48
	v_and_b32_e32 v59, 0xffff0000, v48
	v_add_f32_dpp v16, v16, v16 quad_perm:[1,0,3,2] row_mask:0xf bank_mask:0xf bound_ctrl:1
	v_and_b32_e32 v139, 0xffff0000, v49
	v_lshlrev_b32_e32 v130, 16, v50
	v_add_f32_dpp v16, v16, v16 quad_perm:[2,3,0,1] row_mask:0xf bank_mask:0xf bound_ctrl:1
	v_and_b32_e32 v131, 0xffff0000, v50
	v_lshlrev_b32_e32 v132, 16, v51
	v_add_f32_dpp v16, v16, v16 row_half_mirror row_mask:0xf bank_mask:0xf bound_ctrl:1
	v_and_b32_e32 v133, 0xffff0000, v51
	s_nop 0
	v_add_f32_dpp v16, v16, v16 row_mirror row_mask:0xf bank_mask:0xf bound_ctrl:1
	v_mul_f32_e32 v56, 0x4f800000, v16
	v_cmp_gt_f32_e32 vcc, s3, v16
	s_nop 1
	v_cndmask_b32_e32 v16, v16, v56, vcc
	v_sqrt_f32_e32 v56, v16
	s_nop 0
	v_add_u32_e32 v58, -1, v56
	v_fma_f32 v138, -v58, v56, v16
	v_cmp_ge_f32_e64 s[46:47], 0, v138
	v_add_u32_e32 v138, 1, v56
	s_nop 0
	v_cndmask_b32_e64 v58, v56, v58, s[46:47]
	v_fma_f32 v56, -v138, v56, v16
	v_cmp_lt_f32_e64 s[46:47], 0, v56
	s_nop 1
	v_cndmask_b32_e64 v56, v58, v138, s[46:47]
	v_mul_f32_e32 v58, 0x37800000, v56
	v_cndmask_b32_e32 v56, v56, v58, vcc
	v_cmp_class_f32_e32 vcc, v16, v124
	s_nop 1
	v_cndmask_b32_e32 v16, v56, v16, vcc
	v_max_f32_e32 v16, 0x2b8cbccc, v16
	v_rcp_f32_e32 v138, v16
	v_mul_f32_e32 v16, 0x3fb8aa3b, v57
	v_exp_f32_e32 v58, v16
	v_mul_f32_e32 v16, 0x3fb8aa3b, v59
	v_exp_f32_e32 v59, v16
	v_pk_mul_f32 v[56:57], v[138:139], v[128:129] op_sel_hi:[0,1] neg_lo:[0,1] neg_hi:[0,1]
	v_lshlrev_b32_e32 v16, 16, v49
	v_mul_f32_e32 v16, 0x3fb8aa3b, v16
	ds_write_b128 v125, v[56:59] offset:49152
	v_lshlrev_b32_e32 v56, 16, v46
	v_and_b32_e32 v57, 0xffff0000, v46
	v_pk_add_f32 v[58:59], v[56:57], -1.0 op_sel_hi:[1,0]
	s_nop 0
	v_pk_fma_f32 v[58:59], v[10:11], v[58:59], 1.0 op_sel_hi:[1,1,0]
	s_nop 0
	v_pk_mul_f32 v[58:59], v[58:59], v[126:127]
	s_nop 0
	v_mul_f32_e32 v126, v58, v130
	v_fma_f32 v140, v2, v126, 0
	v_mul_f32_e32 v126, v59, v131
	v_fmac_f32_e32 v140, v3, v126
	v_pk_mul_f32 v[126:127], v[128:129], v[138:139] op_sel_hi:[1,0]
	v_exp_f32_e32 v128, v16
	v_mul_f32_e32 v16, 0x3fb8aa3b, v139
	v_exp_f32_e32 v129, v16
	v_pk_mul_f32 v[56:57], v[126:127], v[56:57]
	ds_write_b128 v125, v[56:59] offset:49168
	v_lshlrev_b32_e32 v58, 16, v47
	v_and_b32_e32 v59, 0xffff0000, v47
	v_pk_add_f32 v[56:57], v[58:59], -1.0 op_sel_hi:[1,0]
	v_pk_mul_f32 v[126:127], v[138:139], v[136:137] op_sel_hi:[0,1] neg_lo:[0,1] neg_hi:[0,1]
	v_pk_fma_f32 v[56:57], v[12:13], v[56:57], 1.0 op_sel_hi:[1,1,0]
	ds_write_b128 v125, v[126:129] offset:49200
	v_pk_mul_f32 v[128:129], v[56:57], v[134:135]
	v_pk_mul_f32 v[126:127], v[136:137], v[138:139] op_sel_hi:[1,0]
	v_mul_f32_e32 v16, v128, v132
	v_mul_f32_e32 v56, v129, v133
	v_fmac_f32_e32 v140, v4, v16
	v_fmac_f32_e32 v140, v5, v56
	v_pk_mul_f32 v[126:127], v[126:127], v[58:59]
	v_add_u32_e32 v57, 0xc000, v125
	v_add_f32_dpp v16, v140, v140 quad_perm:[1,0,3,2] row_mask:0xf bank_mask:0xf bound_ctrl:1
	ds_write_b128 v125, v[126:129] offset:49216
	ds_write2_b64 v57, v[130:131], v[132:133] offset0:4 offset1:10
	v_add_f32_dpp v16, v16, v16 quad_perm:[2,3,0,1] row_mask:0xf bank_mask:0xf bound_ctrl:1
	s_nop 1
	v_add_f32_dpp v16, v16, v16 row_half_mirror row_mask:0xf bank_mask:0xf bound_ctrl:1
	s_nop 1
	v_mov_b32_dpp v56, v16 row_mirror row_mask:0xf bank_mask:0xf bound_ctrl:1
	s_and_saveexec_b64 s[46:47], s[0:1]
	v_lshlrev_b32_e32 v126, 16, v32
	v_and_b32_e32 v127, 0xffff0000, v32
	v_lshlrev_b32_e32 v128, 16, v33
	v_and_b32_e32 v129, 0xffff0000, v33
	ds_write_b128 v15, v[126:129] offset:2048
	s_or_b64 exec, exec, s[46:47]
	s_and_saveexec_b64 s[46:47], s[42:43]
	s_cbranch_execz .LBB0_1630
	v_add_f32_e32 v16, v16, v56
	v_lshl_add_u64 v[56:57], s[52:53], 0, v[38:39]
	v_add_co_u32_e32 v56, vcc, 0x1e501000, v56
	s_nop 1
	v_addc_co_u32_e32 v57, vcc, 0, v57, vcc
	global_store_dword v[56:57], v16, off
.LBB0_1630:
	s_or_b64 exec, exec, s[46:47]
	s_waitcnt lgkmcnt(0)
	s_barrier
	ds_read_b32 v56, v60
	v_lshl_add_u64 v[58:59], s[52:53], 0, v[44:45]
	s_waitcnt lgkmcnt(0)
	v_mul_f32_e32 v57, v56, v56
	v_mov_b32_dpp v126, v56 quad_perm:[1,0,3,2] row_mask:0xf bank_mask:0xf bound_ctrl:1
	s_nop 0
	v_mov_b32_dpp v127, v57 quad_perm:[1,0,3,2] row_mask:0xf bank_mask:0xf bound_ctrl:1
	v_cvt_pk_bf16_f32 v16, v56, s0
	v_pk_add_f32 v[56:57], v[56:57], v[126:127]
	global_store_short v[58:59], v16, off
	s_nop 0
	v_mov_b32_dpp v58, v56 quad_perm:[2,3,0,1] row_mask:0xf bank_mask:0xf bound_ctrl:1
	v_mov_b32_dpp v59, v57 quad_perm:[2,3,0,1] row_mask:0xf bank_mask:0xf bound_ctrl:1
	v_pk_add_f32 v[56:57], v[56:57], v[58:59]
	s_nop 1
	v_mov_b32_dpp v58, v56 row_half_mirror row_mask:0xf bank_mask:0xf bound_ctrl:1
	v_mov_b32_dpp v59, v57 row_half_mirror row_mask:0xf bank_mask:0xf bound_ctrl:1
	v_pk_add_f32 v[56:57], v[56:57], v[58:59]
	s_nop 1
	v_mov_b32_dpp v58, v56 row_mirror row_mask:0xf bank_mask:0xf bound_ctrl:1
	v_mov_b32_dpp v59, v57 row_mirror row_mask:0xf bank_mask:0xf bound_ctrl:1
	s_and_saveexec_b64 s[46:47], s[8:9]
	s_cbranch_execz .LBB0_1632
	v_pk_add_f32 v[56:57], v[56:57], v[58:59]
	v_lshl_add_u64 v[58:59], s[52:53], 0, v[34:35]
	v_add_co_u32_e32 v58, vcc, 0x1d500000, v58
	s_nop 1
	v_addc_co_u32_e32 v59, vcc, 0, v59, vcc
	global_store_dwordx2 v[58:59], v[56:57], off

; __device__ __forceinline__ void wkv_phase(const WkvT& W, unsigned char* lds) {
;     ...
;         for (int c = 0; c < 256; ++c) {
;             const int bi = c & 1, bo = bi * 12288, bn = (bi ^ 1) * 12288;
;             if (c + 1 < 256) wkv_issue(W, raw, rowbase, cbase, q, c + 1, tid);
;             {
;                 const float* pp = sP + bo + jj * 12;
;                 const float* pv = sV + bi * 512 + il;
;                 f32x4 nA = *(const f32x4*)pp, nB = *(const f32x4*)(pp + 4); f32x2 nr = *(const f32x2*)(pp + 8); float nv = pv[0];
;                 float yk0 = 0.f, yk1 = 0.f, ep = 0.f;
;                 const bool oddrow = (lane & 16) != 0;
; #pragma unroll
;                 for (int t = 0; t < 32; ++t) {
;                     const f32x2 a2 = {nA[0], nA[1]}, w2 = {nA[2], nA[3]}, b2 = {nB[0], nB[1]}, k2 = {nB[2], nB[3]}, r2 = nr; const float v = nv;
;                     if (t + 1 < 32) { nA = *(const f32x4*)(pp + (t + 1) * 384); nB = *(const f32x4*)(pp + (t + 1) * 384 + 4); nr = *(const f32x2*)(pp + (t + 1) * 384 + 8); nv = pv[(t + 1) * 16]; }
;                     float S0 = S.x, S1 = S.y;
;                     float d = S0 * a2.x; d = __builtin_fmaf(S1, a2.y, d);
;                     float t0 = S0 * w2.x; t0 = __builtin_fmaf(v, k2.x, t0); asm volatile("" : "+v"(t0));
;                     float t1 = S1 * w2.y; t1 = __builtin_fmaf(v, k2.y, t1); asm volatile("" : "+v"(t1));
;                     float yprev; const float sa = wkv_reduce(d, ep, yprev);
;                     S0 = __builtin_fmaf(sa, b2.x, t0); asm volatile("" : "+v"(S0));
;                     S1 = __builtin_fmaf(sa, b2.y, t1); asm volatile("" : "+v"(S1));
;                     ep = S0 * r2.x; ep = __builtin_fmaf(S1, r2.y, ep);
;                     S.x = S0; S.y = S1;
;                     if (t >= 1) { const bool hit = oddrow && ((lane & 15) == ((t - 1) & 15)); if (t <= 16) yk0 = hit ? yprev : yk0; else yk1 = hit ? yprev : yk1; }
.LBB0_1636:
	v_add_u32_e32 v232, 0x800, v21
	v_add_u32_e32 v233, 0xc00, v21
	v_mov_b32_e32 v145, 0
	v_mov_b32_e32 v148, 0
	ds_read_b128 v[160:163], v19 offset:49152
	ds_read_b128 v[164:167], v19 offset:49168
	ds_read_b64 v[168:169], v19 offset:49184
	ds_read2_b32 v[224:225], v232 offset0:0 offset1:16
	ds_read_b128 v[176:179], v19 offset:50688
	ds_read_b128 v[180:183], v19 offset:50704
	ds_read_b64 v[184:185], v19 offset:50720
	ds_read_b128 v[192:195], v19 offset:52224
	ds_read_b128 v[196:199], v19 offset:52240
	ds_read_b64 v[200:201], v19 offset:52256
	ds_read2_b32 v[226:227], v232 offset0:32 offset1:48
	s_waitcnt lgkmcnt(7)
	v_mul_f32_e32 v144, v142, v160
	v_fmac_f32_e32 v144, v143, v161
	v_pk_mul_f32 v[150:151], v[142:143], v[162:163]
	s_nop 0
	v_permlane16_swap_b32_e32 v144, v145
	v_add_f32_e32 v144, v144, v145
	v_pk_fma_f32 v[150:151], v[224:225], v[166:167], v[150:151] op_sel:[0,0,0] op_sel_hi:[0,1,1]
	s_nop 0
	v_add_f32_dpp v144, v144, v144 quad_perm:[1,0,3,2] row_mask:0xf bank_mask:0xf bound_ctrl:1
	ds_read_b128 v[208:211], v19 offset:53760
	ds_read_b128 v[212:215], v19 offset:53776
	v_add_f32_dpp v144, v144, v144 quad_perm:[2,3,0,1] row_mask:0xf bank_mask:0xf bound_ctrl:1
	ds_read_b64 v[216:217], v19 offset:53792
	s_nop 0
	v_add_f32_dpp v144, v144, v144 row_half_mirror row_mask:0xf bank_mask:0xf bound_ctrl:1
	s_waitcnt lgkmcnt(7)
	s_nop 0
	v_add_f32_dpp v144, v144, v144 row_mirror row_mask:0xf bank_mask:0xf bound_ctrl:1
	s_nop 1
	v_mov_b32_dpp v144, v144 row_bcast:15 row_mask:0xa bank_mask:0xf
	v_pk_fma_f32 v[150:151], v[144:145], v[164:165], v[150:151] op_sel_hi:[0,1,1]
	v_mul_f32_e32 v144, v150, v176
	v_mul_f32_e32 v145, v150, v168
	v_fmac_f32_e32 v144, v151, v177
	v_fmac_f32_e32 v145, v151, v169
	v_pk_mul_f32 v[152:153], v[150:151], v[178:179]
	s_nop 0
	v_permlane16_swap_b32_e32 v144, v145
	v_add_f32_e32 v144, v144, v145
	v_pk_fma_f32 v[152:153], v[224:225], v[182:183], v[152:153] op_sel:[1,0,0] op_sel_hi:[1,1,1]
	s_nop 0
	v_add_f32_dpp v144, v144, v144 quad_perm:[1,0,3,2] row_mask:0xf bank_mask:0xf bound_ctrl:1
	ds_read_b128 v[160:163], v19 offset:55296
	ds_read_b128 v[164:167], v19 offset:55312
	v_add_f32_dpp v144, v144, v144 quad_perm:[2,3,0,1] row_mask:0xf bank_mask:0xf bound_ctrl:1
	ds_read_b64 v[168:169], v19 offset:55328
	ds_read2_b32 v[228:229], v232 offset0:64 offset1:80
	v_add_f32_dpp v144, v144, v144 row_half_mirror row_mask:0xf bank_mask:0xf bound_ctrl:1
	s_waitcnt lgkmcnt(7)
	s_nop 0
	v_add_f32_dpp v144, v144, v144 row_mirror row_mask:0xf bank_mask:0xf bound_ctrl:1
	v_cndmask_b32_e64 v146, v146, v144, s[10:11]
	s_nop 0
	v_mov_b32_dpp v144, v144 row_bcast:15 row_mask:0xa bank_mask:0xf
	v_pk_fma_f32 v[152:153], v[144:145], v[180:181], v[152:153] op_sel_hi:[0,1,1]
	v_mul_f32_e32 v144, v152, v192
	v_mul_f32_e32 v145, v152, v184
	v_fmac_f32_e32 v144, v153, v193
	v_fmac_f32_e32 v145, v153, v185
	v_pk_mul_f32 v[150:151], v[152:153], v[194:195]
	s_nop 0
	v_permlane16_swap_b32_e32 v144, v145
	v_add_f32_e32 v144, v144, v145
	v_pk_fma_f32 v[150:151], v[226:227], v[198:199], v[150:151] op_sel:[0,0,0] op_sel_hi:[0,1,1]
	s_nop 0
	v_add_f32_dpp v144, v144, v144 quad_perm:[1,0,3,2] row_mask:0xf bank_mask:0xf bound_ctrl:1
	ds_read_b128 v[176:179], v19 offset:56832
	ds_read_b128 v[180:183], v19 offset:56848
	v_add_f32_dpp v144, v144, v144 quad_perm:[2,3,0,1] row_mask:0xf bank_mask:0xf bound_ctrl:1
	ds_read_b64 v[184:185], v19 offset:56864
	s_nop 0
	v_add_f32_dpp v144, v144, v144 row_half_mirror row_mask:0xf bank_mask:0xf bound_ctrl:1
	s_waitcnt lgkmcnt(7)
	s_nop 0
	v_add_f32_dpp v144, v144, v144 row_mirror row_mask:0xf bank_mask:0xf bound_ctrl:1
	v_cndmask_b32_e64 v146, v146, v144, s[12:13]
	s_nop 0
	v_mov_b32_dpp v144, v144 row_bcast:15 row_mask:0xa bank_mask:0xf
	v_pk_fma_f32 v[150:151], v[144:145], v[196:197], v[150:151] op_sel_hi:[0,1,1]
	v_mul_f32_e32 v144, v150, v208
	v_mul_f32_e32 v145, v150, v200
	v_fmac_f32_e32 v144, v151, v209
	v_fmac_f32_e32 v145, v151, v201
	v_pk_mul_f32 v[152:153], v[150:151], v[210:211]
	s_nop 0
	v_permlane16_swap_b32_e32 v144, v145
	v_add_f32_e32 v144, v144, v145
	v_pk_fma_f32 v[152:153], v[226:227], v[214:215], v[152:153] op_sel:[1,0,0] op_sel_hi:[1,1,1]
	s_nop 0
	v_add_f32_dpp v144, v144, v144 quad_perm:[1,0,3,2] row_mask:0xf bank_mask:0xf bound_ctrl:1
	ds_read_b128 v[192:195], v19 offset:58368
	ds_read_b128 v[196:199], v19 offset:58384
	v_add_f32_dpp v144, v144, v144 quad_perm:[2,3,0,1] row_mask:0xf bank_mask:0xf bound_ctrl:1
	ds_read_b64 v[200:201], v19 offset:58400
	ds_read2_b32 v[230:231], v232 offset0:96 offset1:112
	v_add_f32_dpp v144, v144, v144 row_half_mirror row_mask:0xf bank_mask:0xf bound_ctrl:1
	s_waitcnt lgkmcnt(7)
	s_nop 0
	v_add_f32_dpp v144, v144, v144 row_mirror row_mask:0xf bank_mask:0xf bound_ctrl:1
	v_cndmask_b32_e64 v146, v146, v144, s[14:15]
	s_nop 0
	v_mov_b32_dpp v144, v144 row_bcast:15 row_mask:0xa bank_mask:0xf
	v_pk_fma_f32 v[152:153], v[144:145], v[212:213], v[152:153] op_sel_hi:[0,1,1]
	v_mul_f32_e32 v144, v152, v160
	v_mul_f32_e32 v145, v152, v216
	v_fmac_f32_e32 v144, v153, v161
	v_fmac_f32_e32 v145, v153, v217
	v_pk_mul_f32 v[150:151], v[152:153], v[162:163]
	s_nop 0
	v_permlane16_swap_b32_e32 v144, v145
	v_add_f32_e32 v144, v144, v145
	v_pk_fma_f32 v[150:151], v[228:229], v[166:167], v[150:151] op_sel:[0,0,0] op_sel_hi:[0,1,1]
	s_nop 0
	v_add_f32_dpp v144, v144, v144 quad_perm:[1,0,3,2] row_mask:0xf bank_mask:0xf bound_ctrl:1
	ds_read_b128 v[208:211], v19 offset:59904
	ds_read_b128 v[212:215], v19 offset:59920
	v_add_f32_dpp v144, v144, v144 quad_perm:[2,3,0,1] row_mask:0xf bank_mask:0xf bound_ctrl:1
	ds_read_b64 v[216:217], v19 offset:59936
	s_nop 0
	v_add_f32_dpp v144, v144, v144 row_half_mirror row_mask:0xf bank_mask:0xf bound_ctrl:1
	s_waitcnt lgkmcnt(7)
; __device__ __forceinline__ float wkv_reduce(float x, float y, float& zy) {
;     auto f = __builtin_amdgcn_permlane16_swap(__float_as_uint(x), __float_as_uint(y), false, false);
;     float z = __uint_as_float(f[0]) + __uint_as_float(f[1]);
;     z += dpp_f(z, 0); z += dpp_f(z, 1); z += dpp_f(z, 2); z += dpp_f(z, 3);
;     zy = z;
;     const int zi = __builtin_bit_cast(int, z);
;     return __builtin_bit_cast(float, __builtin_amdgcn_update_dpp(zi, zi, 0x142, 0xA, 0xF, false));
; }
; __device__ __forceinline__ void wkv_phase(const WkvT& W, unsigned char* lds) {
;     ...
;                 for (int t = 0; t < 32; ++t) {
;                     const f32x2 a2 = {nA[0], nA[1]}, w2 = {nA[2], nA[3]}, b2 = {nB[0], nB[1]}, k2 = {nB[2], nB[3]}, r2 = nr; const float v = nv;
;                     if (t + 1 < 32) { nA = *(const f32x4*)(pp + (t + 1) * 384); nB = *(const f32x4*)(pp + (t + 1) * 384 + 4); nr = *(const f32x2*)(pp + (t + 1) * 384 + 8); nv = pv[(t + 1) * 16]; }
;                     float S0 = S.x, S1 = S.y;
;                     float d = S0 * a2.x; d = __builtin_fmaf(S1, a2.y, d);
;                     float t0 = S0 * w2.x; t0 = __builtin_fmaf(v, k2.x, t0); asm volatile("" : "+v"(t0));
;                     float t1 = S1 * w2.y; t1 = __builtin_fmaf(v, k2.y, t1); asm volatile("" : "+v"(t1));
;                     float yprev; const float sa = wkv_reduce(d, ep, yprev);
;                     S0 = __builtin_fmaf(sa, b2.x, t0); asm volatile("" : "+v"(S0));
;                     S1 = __builtin_fmaf(sa, b2.y, t1); asm volatile("" : "+v"(S1));
;                     ep = S0 * r2.x; ep = __builtin_fmaf(S1, r2.y, ep);
;                     S.x = S0; S.y = S1;
;                     if (t >= 1) { const bool hit = oddrow && ((lane & 15) == ((t - 1) & 15)); if (t <= 16) yk0 = hit ? yprev : yk0; else yk1 = hit ? yprev : yk1; }
	s_nop 0
	v_add_f32_dpp v144, v144, v144 row_mirror row_mask:0xf bank_mask:0xf bound_ctrl:1
	v_cndmask_b32_e64 v146, v146, v144, s[16:17]
	s_nop 0
	v_mov_b32_dpp v144, v144 row_bcast:15 row_mask:0xa bank_mask:0xf
	v_pk_fma_f32 v[150:151], v[144:145], v[164:165], v[150:151] op_sel_hi:[0,1,1]
	v_mul_f32_e32 v144, v150, v176
	v_mul_f32_e32 v145, v150, v168
	v_fmac_f32_e32 v144, v151, v177
	v_fmac_f32_e32 v145, v151, v169
	v_pk_mul_f32 v[152:153], v[150:151], v[178:179]
	s_nop 0
	v_permlane16_swap_b32_e32 v144, v145
	v_add_f32_e32 v144, v144, v145
	v_pk_fma_f32 v[152:153], v[228:229], v[182:183], v[152:153] op_sel:[1,0,0] op_sel_hi:[1,1,1]
	s_nop 0
	v_add_f32_dpp v144, v144, v144 quad_perm:[1,0,3,2] row_mask:0xf bank_mask:0xf bound_ctrl:1
	ds_read_b128 v[160:163], v19 offset:61440
	ds_read_b128 v[164:167], v19 offset:61456
	v_add_f32_dpp v144, v144, v144 quad_perm:[2,3,0,1] row_mask:0xf bank_mask:0xf bound_ctrl:1
	ds_read_b64 v[168:169], v19 offset:61472
	ds_read2_b32 v[224:225], v232 offset0:128 offset1:144
	v_add_f32_dpp v144, v144, v144 row_half_mirror row_mask:0xf bank_mask:0xf bound_ctrl:1
	s_waitcnt lgkmcnt(7)
	s_nop 0
	v_add_f32_dpp v144, v144, v144 row_mirror row_mask:0xf bank_mask:0xf bound_ctrl:1
	v_cndmask_b32_e64 v146, v146, v144, s[18:19]
	s_nop 0
	v_mov_b32_dpp v144, v144 row_bcast:15 row_mask:0xa bank_mask:0xf
	v_pk_fma_f32 v[152:153], v[144:145], v[180:181], v[152:153] op_sel_hi:[0,1,1]
	v_mul_f32_e32 v144, v152, v192
	v_mul_f32_e32 v145, v152, v184
	v_fmac_f32_e32 v144, v153, v193
	v_fmac_f32_e32 v145, v153, v185
	v_pk_mul_f32 v[150:151], v[152:153], v[194:195]
	s_nop 0
	v_permlane16_swap_b32_e32 v144, v145
	v_add_f32_e32 v144, v144, v145
	v_pk_fma_f32 v[150:151], v[230:231], v[198:199], v[150:151] op_sel:[0,0,0] op_sel_hi:[0,1,1]
	s_nop 0
	v_add_f32_dpp v144, v144, v144 quad_perm:[1,0,3,2] row_mask:0xf bank_mask:0xf bound_ctrl:1
	ds_read_b128 v[176:179], v19 offset:62976
	ds_read_b128 v[180:183], v19 offset:62992
	v_add_f32_dpp v144, v144, v144 quad_perm:[2,3,0,1] row_mask:0xf bank_mask:0xf bound_ctrl:1
	ds_read_b64 v[184:185], v19 offset:63008
	s_nop 0
	v_add_f32_dpp v144, v144, v144 row_half_mirror row_mask:0xf bank_mask:0xf bound_ctrl:1
	s_waitcnt lgkmcnt(7)
	s_nop 0
	v_add_f32_dpp v144, v144, v144 row_mirror row_mask:0xf bank_mask:0xf bound_ctrl:1
	v_cndmask_b32_e64 v146, v146, v144, s[20:21]
	s_nop 0
	v_mov_b32_dpp v144, v144 row_bcast:15 row_mask:0xa bank_mask:0xf
	v_pk_fma_f32 v[150:151], v[144:145], v[196:197], v[150:151] op_sel_hi:[0,1,1]
	v_mul_f32_e32 v144, v150, v208
	v_mul_f32_e32 v145, v150, v200
	v_fmac_f32_e32 v144, v151, v209
	v_fmac_f32_e32 v145, v151, v201
	v_pk_mul_f32 v[152:153], v[150:151], v[210:211]
	s_nop 0
	v_permlane16_swap_b32_e32 v144, v145
	v_add_f32_e32 v144, v144, v145
	v_pk_fma_f32 v[152:153], v[230:231], v[214:215], v[152:153] op_sel:[1,0,0] op_sel_hi:[1,1,1]
	s_nop 0
	v_add_f32_dpp v144, v144, v144 quad_perm:[1,0,3,2] row_mask:0xf bank_mask:0xf bound_ctrl:1
	ds_read_b128 v[192:195], v19 offset:64512
	ds_read_b128 v[196:199], v19 offset:64528
	v_add_f32_dpp v144, v144, v144 quad_perm:[2,3,0,1] row_mask:0xf bank_mask:0xf bound_ctrl:1
	ds_read_b64 v[200:201], v19 offset:64544
	ds_read2_b32 v[226:227], v232 offset0:160 offset1:176
	v_add_f32_dpp v144, v144, v144 row_half_mirror row_mask:0xf bank_mask:0xf bound_ctrl:1
	s_waitcnt lgkmcnt(7)
	s_nop 0
	v_add_f32_dpp v144, v144, v144 row_mirror row_mask:0xf bank_mask:0xf bound_ctrl:1
	v_cndmask_b32_e64 v146, v146, v144, s[22:23]
	s_nop 0
	v_mov_b32_dpp v144, v144 row_bcast:15 row_mask:0xa bank_mask:0xf
	v_pk_fma_f32 v[152:153], v[144:145], v[212:213], v[152:153] op_sel_hi:[0,1,1]
	v_mul_f32_e32 v144, v152, v160
	v_mul_f32_e32 v145, v152, v216
	v_fmac_f32_e32 v144, v153, v161
	v_fmac_f32_e32 v145, v153, v217
	v_pk_mul_f32 v[150:151], v[152:153], v[162:163]
	s_nop 0
	v_permlane16_swap_b32_e32 v144, v145
	v_add_f32_e32 v144, v144, v145
	v_pk_fma_f32 v[150:151], v[224:225], v[166:167], v[150:151] op_sel:[0,0,0] op_sel_hi:[0,1,1]
	s_nop 0
	v_add_f32_dpp v144, v144, v144 quad_perm:[1,0,3,2] row_mask:0xf bank_mask:0xf bound_ctrl:1
	ds_read_b128 v[208:211], v61
	ds_read_b128 v[212:215], v61 offset:16
	v_add_f32_dpp v144, v144, v144 quad_perm:[2,3,0,1] row_mask:0xf bank_mask:0xf bound_ctrl:1
	ds_read_b64 v[216:217], v61 offset:32
	s_nop 0
	v_add_f32_dpp v144, v144, v144 row_half_mirror row_mask:0xf bank_mask:0xf bound_ctrl:1
	s_waitcnt lgkmcnt(7)
	s_nop 0
	v_add_f32_dpp v144, v144, v144 row_mirror row_mask:0xf bank_mask:0xf bound_ctrl:1
	v_cndmask_b32_e64 v146, v146, v144, s[24:25]
	s_nop 0
	v_mov_b32_dpp v144, v144 row_bcast:15 row_mask:0xa bank_mask:0xf
	v_pk_fma_f32 v[150:151], v[144:145], v[164:165], v[150:151] op_sel_hi:[0,1,1]
	v_mul_f32_e32 v144, v150, v176
	v_mul_f32_e32 v145, v150, v168
	v_fmac_f32_e32 v144, v151, v177
	v_fmac_f32_e32 v145, v151, v169
	v_pk_mul_f32 v[152:153], v[150:151], v[178:179]
	s_nop 0
	v_permlane16_swap_b32_e32 v144, v145
	v_add_f32_e32 v144, v144, v145
	v_pk_fma_f32 v[152:153], v[224:225], v[182:183], v[152:153] op_sel:[1,0,0] op_sel_hi:[1,1,1]
	s_nop 0
	v_add_f32_dpp v144, v144, v144 quad_perm:[1,0,3,2] row_mask:0xf bank_mask:0xf bound_ctrl:1
	ds_read_b128 v[160:163], v61 offset:1536
	ds_read_b128 v[164:167], v61 offset:1552
	v_add_f32_dpp v144, v144, v144 quad_perm:[2,3,0,1] row_mask:0xf bank_mask:0xf bound_ctrl:1
	ds_read_b64 v[168:169], v61 offset:1568
	ds_read2_b32 v[228:229], v232 offset0:192 offset1:208
	v_add_f32_dpp v144, v144, v144 row_half_mirror row_mask:0xf bank_mask:0xf bound_ctrl:1
	s_waitcnt lgkmcnt(7)
; __device__ __forceinline__ float wkv_reduce(float x, float y, float& zy) {
;     auto f = __builtin_amdgcn_permlane16_swap(__float_as_uint(x), __float_as_uint(y), false, false);
;     float z = __uint_as_float(f[0]) + __uint_as_float(f[1]);
;     z += dpp_f(z, 0); z += dpp_f(z, 1); z += dpp_f(z, 2); z += dpp_f(z, 3);
;     zy = z;
;     const int zi = __builtin_bit_cast(int, z);
;     return __builtin_bit_cast(float, __builtin_amdgcn_update_dpp(zi, zi, 0x142, 0xA, 0xF, false));
; }
; __device__ __forceinline__ void wkv_phase(const WkvT& W, unsigned char* lds) {
;     ...
;                 for (int t = 0; t < 32; ++t) {
;                     const f32x2 a2 = {nA[0], nA[1]}, w2 = {nA[2], nA[3]}, b2 = {nB[0], nB[1]}, k2 = {nB[2], nB[3]}, r2 = nr; const float v = nv;
;                     if (t + 1 < 32) { nA = *(const f32x4*)(pp + (t + 1) * 384); nB = *(const f32x4*)(pp + (t + 1) * 384 + 4); nr = *(const f32x2*)(pp + (t + 1) * 384 + 8); nv = pv[(t + 1) * 16]; }
;                     float S0 = S.x, S1 = S.y;
;                     float d = S0 * a2.x; d = __builtin_fmaf(S1, a2.y, d);
;                     float t0 = S0 * w2.x; t0 = __builtin_fmaf(v, k2.x, t0); asm volatile("" : "+v"(t0));
;                     float t1 = S1 * w2.y; t1 = __builtin_fmaf(v, k2.y, t1); asm volatile("" : "+v"(t1));
;                     float yprev; const float sa = wkv_reduce(d, ep, yprev);
;                     S0 = __builtin_fmaf(sa, b2.x, t0); asm volatile("" : "+v"(S0));
;                     S1 = __builtin_fmaf(sa, b2.y, t1); asm volatile("" : "+v"(S1));
;                     ep = S0 * r2.x; ep = __builtin_fmaf(S1, r2.y, ep);
;                     S.x = S0; S.y = S1;
;                     if (t >= 1) { const bool hit = oddrow && ((lane & 15) == ((t - 1) & 15)); if (t <= 16) yk0 = hit ? yprev : yk0; else yk1 = hit ? yprev : yk1; }
	s_nop 0
	v_add_f32_dpp v144, v144, v144 row_mirror row_mask:0xf bank_mask:0xf bound_ctrl:1
	v_cndmask_b32_e64 v146, v146, v144, s[26:27]
	s_nop 0
	v_mov_b32_dpp v144, v144 row_bcast:15 row_mask:0xa bank_mask:0xf
	v_pk_fma_f32 v[152:153], v[144:145], v[180:181], v[152:153] op_sel_hi:[0,1,1]
	v_mul_f32_e32 v144, v152, v192
	v_mul_f32_e32 v145, v152, v184
	v_fmac_f32_e32 v144, v153, v193
	v_fmac_f32_e32 v145, v153, v185
	v_pk_mul_f32 v[150:151], v[152:153], v[194:195]
	s_nop 0
	v_permlane16_swap_b32_e32 v144, v145
	v_add_f32_e32 v144, v144, v145
	v_pk_fma_f32 v[150:151], v[226:227], v[198:199], v[150:151] op_sel:[0,0,0] op_sel_hi:[0,1,1]
	s_nop 0
	v_add_f32_dpp v144, v144, v144 quad_perm:[1,0,3,2] row_mask:0xf bank_mask:0xf bound_ctrl:1
	ds_read_b128 v[176:179], v61 offset:3072
	ds_read_b128 v[180:183], v61 offset:3088
	v_add_f32_dpp v144, v144, v144 quad_perm:[2,3,0,1] row_mask:0xf bank_mask:0xf bound_ctrl:1
	ds_read_b64 v[184:185], v61 offset:3104
	s_nop 0
	v_add_f32_dpp v144, v144, v144 row_half_mirror row_mask:0xf bank_mask:0xf bound_ctrl:1
	s_waitcnt lgkmcnt(7)
	s_nop 0
	v_add_f32_dpp v144, v144, v144 row_mirror row_mask:0xf bank_mask:0xf bound_ctrl:1
	v_cndmask_b32_e64 v146, v146, v144, s[28:29]
	s_nop 0
	v_mov_b32_dpp v144, v144 row_bcast:15 row_mask:0xa bank_mask:0xf
	v_pk_fma_f32 v[150:151], v[144:145], v[196:197], v[150:151] op_sel_hi:[0,1,1]
	v_mul_f32_e32 v144, v150, v208
	v_mul_f32_e32 v145, v150, v200
	v_fmac_f32_e32 v144, v151, v209
	v_fmac_f32_e32 v145, v151, v201
	v_pk_mul_f32 v[152:153], v[150:151], v[210:211]
	s_nop 0
	v_permlane16_swap_b32_e32 v144, v145
	v_add_f32_e32 v144, v144, v145
	v_pk_fma_f32 v[152:153], v[226:227], v[214:215], v[152:153] op_sel:[1,0,0] op_sel_hi:[1,1,1]
	s_nop 0
	v_add_f32_dpp v144, v144, v144 quad_perm:[1,0,3,2] row_mask:0xf bank_mask:0xf bound_ctrl:1
	ds_read_b128 v[192:195], v61 offset:4608
	ds_read_b128 v[196:199], v61 offset:4624
	v_add_f32_dpp v144, v144, v144 quad_perm:[2,3,0,1] row_mask:0xf bank_mask:0xf bound_ctrl:1
	ds_read_b64 v[200:201], v61 offset:4640
	ds_read2_b32 v[230:231], v232 offset0:224 offset1:240
	v_add_f32_dpp v144, v144, v144 row_half_mirror row_mask:0xf bank_mask:0xf bound_ctrl:1
	s_waitcnt lgkmcnt(7)
	s_nop 0
	v_add_f32_dpp v144, v144, v144 row_mirror row_mask:0xf bank_mask:0xf bound_ctrl:1
	v_cndmask_b32_e64 v146, v146, v144, s[30:31]
	s_nop 0
	v_mov_b32_dpp v144, v144 row_bcast:15 row_mask:0xa bank_mask:0xf
	v_pk_fma_f32 v[152:153], v[144:145], v[212:213], v[152:153] op_sel_hi:[0,1,1]
	v_mul_f32_e32 v144, v152, v160
	v_mul_f32_e32 v145, v152, v216
	v_fmac_f32_e32 v144, v153, v161
	v_fmac_f32_e32 v145, v153, v217
	v_pk_mul_f32 v[150:151], v[152:153], v[162:163]
	s_nop 0
	v_permlane16_swap_b32_e32 v144, v145
	v_add_f32_e32 v144, v144, v145
	v_pk_fma_f32 v[150:151], v[228:229], v[166:167], v[150:151] op_sel:[0,0,0] op_sel_hi:[0,1,1]
	s_nop 0
	v_add_f32_dpp v144, v144, v144 quad_perm:[1,0,3,2] row_mask:0xf bank_mask:0xf bound_ctrl:1
	ds_read_b128 v[208:211], v61 offset:6144
	ds_read_b128 v[212:215], v61 offset:6160
	v_add_f32_dpp v144, v144, v144 quad_perm:[2,3,0,1] row_mask:0xf bank_mask:0xf bound_ctrl:1
	ds_read_b64 v[216:217], v61 offset:6176
	s_nop 0
	v_add_f32_dpp v144, v144, v144 row_half_mirror row_mask:0xf bank_mask:0xf bound_ctrl:1
	s_waitcnt lgkmcnt(7)
	s_nop 0
	v_add_f32_dpp v144, v144, v144 row_mirror row_mask:0xf bank_mask:0xf bound_ctrl:1
	v_cndmask_b32_e64 v146, v146, v144, s[34:35]
	s_nop 0
	v_mov_b32_dpp v144, v144 row_bcast:15 row_mask:0xa bank_mask:0xf
	v_pk_fma_f32 v[150:151], v[144:145], v[164:165], v[150:151] op_sel_hi:[0,1,1]
	v_mul_f32_e32 v144, v150, v176
	v_mul_f32_e32 v145, v150, v168
	v_fmac_f32_e32 v144, v151, v177
	v_fmac_f32_e32 v145, v151, v169
	v_pk_mul_f32 v[152:153], v[150:151], v[178:179]
	s_nop 0
	v_permlane16_swap_b32_e32 v144, v145
	v_add_f32_e32 v144, v144, v145
	v_pk_fma_f32 v[152:153], v[228:229], v[182:183], v[152:153] op_sel:[1,0,0] op_sel_hi:[1,1,1]
	s_nop 0
	v_add_f32_dpp v144, v144, v144 quad_perm:[1,0,3,2] row_mask:0xf bank_mask:0xf bound_ctrl:1
	ds_read_b128 v[160:163], v61 offset:7680
	ds_read_b128 v[164:167], v61 offset:7696
	v_add_f32_dpp v144, v144, v144 quad_perm:[2,3,0,1] row_mask:0xf bank_mask:0xf bound_ctrl:1
	ds_read_b64 v[168:169], v61 offset:7712
	ds_read2_b32 v[224:225], v233 offset0:0 offset1:16
	v_add_f32_dpp v144, v144, v144 row_half_mirror row_mask:0xf bank_mask:0xf bound_ctrl:1
	s_waitcnt lgkmcnt(7)
	s_nop 0
	v_add_f32_dpp v144, v144, v144 row_mirror row_mask:0xf bank_mask:0xf bound_ctrl:1
	v_cndmask_b32_e64 v146, v146, v144, s[36:37]
	s_nop 0
	v_mov_b32_dpp v144, v144 row_bcast:15 row_mask:0xa bank_mask:0xf
	v_pk_fma_f32 v[152:153], v[144:145], v[180:181], v[152:153] op_sel_hi:[0,1,1]
	v_mul_f32_e32 v144, v152, v192
	v_mul_f32_e32 v145, v152, v184
	v_fmac_f32_e32 v144, v153, v193
	v_fmac_f32_e32 v145, v153, v185
	v_pk_mul_f32 v[150:151], v[152:153], v[194:195]
	s_nop 0
	v_permlane16_swap_b32_e32 v144, v145
	v_add_f32_e32 v144, v144, v145
	v_pk_fma_f32 v[150:151], v[230:231], v[198:199], v[150:151] op_sel:[0,0,0] op_sel_hi:[0,1,1]
	s_nop 0
	v_add_f32_dpp v144, v144, v144 quad_perm:[1,0,3,2] row_mask:0xf bank_mask:0xf bound_ctrl:1
	ds_read_b128 v[176:179], v61 offset:9216
	ds_read_b128 v[180:183], v61 offset:9232
	v_add_f32_dpp v144, v144, v144 quad_perm:[2,3,0,1] row_mask:0xf bank_mask:0xf bound_ctrl:1
	ds_read_b64 v[184:185], v61 offset:9248
	s_nop 0
	v_add_f32_dpp v144, v144, v144 row_half_mirror row_mask:0xf bank_mask:0xf bound_ctrl:1
	s_waitcnt lgkmcnt(7)
; __device__ __forceinline__ float wkv_reduce(float x, float y, float& zy) {
;     auto f = __builtin_amdgcn_permlane16_swap(__float_as_uint(x), __float_as_uint(y), false, false);
;     float z = __uint_as_float(f[0]) + __uint_as_float(f[1]);
;     z += dpp_f(z, 0); z += dpp_f(z, 1); z += dpp_f(z, 2); z += dpp_f(z, 3);
;     zy = z;
;     const int zi = __builtin_bit_cast(int, z);
;     return __builtin_bit_cast(float, __builtin_amdgcn_update_dpp(zi, zi, 0x142, 0xA, 0xF, false));
; }
; __device__ __forceinline__ void wkv_phase(const WkvT& W, unsigned char* lds) {
;     ...
;                 for (int t = 0; t < 32; ++t) {
;                     const f32x2 a2 = {nA[0], nA[1]}, w2 = {nA[2], nA[3]}, b2 = {nB[0], nB[1]}, k2 = {nB[2], nB[3]}, r2 = nr; const float v = nv;
;                     if (t + 1 < 32) { nA = *(const f32x4*)(pp + (t + 1) * 384); nB = *(const f32x4*)(pp + (t + 1) * 384 + 4); nr = *(const f32x2*)(pp + (t + 1) * 384 + 8); nv = pv[(t + 1) * 16]; }
;                     float S0 = S.x, S1 = S.y;
;                     float d = S0 * a2.x; d = __builtin_fmaf(S1, a2.y, d);
;                     float t0 = S0 * w2.x; t0 = __builtin_fmaf(v, k2.x, t0); asm volatile("" : "+v"(t0));
;                     float t1 = S1 * w2.y; t1 = __builtin_fmaf(v, k2.y, t1); asm volatile("" : "+v"(t1));
;                     float yprev; const float sa = wkv_reduce(d, ep, yprev);
;                     S0 = __builtin_fmaf(sa, b2.x, t0); asm volatile("" : "+v"(S0));
;                     S1 = __builtin_fmaf(sa, b2.y, t1); asm volatile("" : "+v"(S1));
;                     ep = S0 * r2.x; ep = __builtin_fmaf(S1, r2.y, ep);
;                     S.x = S0; S.y = S1;
;                     if (t >= 1) { const bool hit = oddrow && ((lane & 15) == ((t - 1) & 15)); if (t <= 16) yk0 = hit ? yprev : yk0; else yk1 = hit ? yprev : yk1; }
	s_nop 0
	v_add_f32_dpp v144, v144, v144 row_mirror row_mask:0xf bank_mask:0xf bound_ctrl:1
	v_cndmask_b32_e64 v146, v146, v144, s[38:39]
	s_nop 0
	v_mov_b32_dpp v144, v144 row_bcast:15 row_mask:0xa bank_mask:0xf
	v_pk_fma_f32 v[150:151], v[144:145], v[196:197], v[150:151] op_sel_hi:[0,1,1]
	v_mul_f32_e32 v144, v150, v208
	v_mul_f32_e32 v145, v150, v200
	v_fmac_f32_e32 v144, v151, v209
	v_fmac_f32_e32 v145, v151, v201
	v_pk_mul_f32 v[152:153], v[150:151], v[210:211]
	s_nop 0
	v_permlane16_swap_b32_e32 v144, v145
	v_add_f32_e32 v144, v144, v145
	v_pk_fma_f32 v[152:153], v[230:231], v[214:215], v[152:153] op_sel:[1,0,0] op_sel_hi:[1,1,1]
	s_nop 0
	v_add_f32_dpp v144, v144, v144 quad_perm:[1,0,3,2] row_mask:0xf bank_mask:0xf bound_ctrl:1
	ds_read_b128 v[192:195], v61 offset:10752
	ds_read_b128 v[196:199], v61 offset:10768
	v_add_f32_dpp v144, v144, v144 quad_perm:[2,3,0,1] row_mask:0xf bank_mask:0xf bound_ctrl:1
	ds_read_b64 v[200:201], v61 offset:10784
	ds_read2_b32 v[226:227], v233 offset0:32 offset1:48
	v_add_f32_dpp v144, v144, v144 row_half_mirror row_mask:0xf bank_mask:0xf bound_ctrl:1
	s_waitcnt lgkmcnt(7)
	s_nop 0
	v_add_f32_dpp v144, v144, v144 row_mirror row_mask:0xf bank_mask:0xf bound_ctrl:1
	v_cndmask_b32_e64 v146, v146, v144, s[40:41]
	s_nop 0
	v_mov_b32_dpp v144, v144 row_bcast:15 row_mask:0xa bank_mask:0xf
	v_pk_fma_f32 v[152:153], v[144:145], v[212:213], v[152:153] op_sel_hi:[0,1,1]
	v_mul_f32_e32 v144, v152, v160
	v_mul_f32_e32 v145, v152, v216
	v_fmac_f32_e32 v144, v153, v161
	v_fmac_f32_e32 v145, v153, v217
	v_pk_mul_f32 v[150:151], v[152:153], v[162:163]
	s_nop 0
	v_permlane16_swap_b32_e32 v144, v145
	v_add_f32_e32 v144, v144, v145
	v_pk_fma_f32 v[150:151], v[224:225], v[166:167], v[150:151] op_sel:[0,0,0] op_sel_hi:[0,1,1]
	s_nop 0
	v_add_f32_dpp v144, v144, v144 quad_perm:[1,0,3,2] row_mask:0xf bank_mask:0xf bound_ctrl:1
	ds_read_b128 v[208:211], v61 offset:12288
	ds_read_b128 v[212:215], v61 offset:12304
	v_add_f32_dpp v144, v144, v144 quad_perm:[2,3,0,1] row_mask:0xf bank_mask:0xf bound_ctrl:1
	ds_read_b64 v[216:217], v61 offset:12320
	s_nop 0
	v_add_f32_dpp v144, v144, v144 row_half_mirror row_mask:0xf bank_mask:0xf bound_ctrl:1
	s_waitcnt lgkmcnt(7)
	s_nop 0
	v_add_f32_dpp v144, v144, v144 row_mirror row_mask:0xf bank_mask:0xf bound_ctrl:1
	v_cndmask_b32_e64 v146, v146, v144, s[6:7]
	s_nop 0
	v_mov_b32_dpp v144, v144 row_bcast:15 row_mask:0xa bank_mask:0xf
	v_pk_fma_f32 v[150:151], v[144:145], v[164:165], v[150:151] op_sel_hi:[0,1,1]
	v_mul_f32_e32 v144, v150, v176
	v_mul_f32_e32 v145, v150, v168
	v_fmac_f32_e32 v144, v151, v177
	v_fmac_f32_e32 v145, v151, v169
	v_pk_mul_f32 v[152:153], v[150:151], v[178:179]
	s_nop 0
	v_permlane16_swap_b32_e32 v144, v145
	v_add_f32_e32 v144, v144, v145
	v_pk_fma_f32 v[152:153], v[224:225], v[182:183], v[152:153] op_sel:[1,0,0] op_sel_hi:[1,1,1]
	s_nop 0
	v_add_f32_dpp v144, v144, v144 quad_perm:[1,0,3,2] row_mask:0xf bank_mask:0xf bound_ctrl:1
	ds_read_b128 v[160:163], v61 offset:13824
	ds_read_b128 v[164:167], v61 offset:13840
	v_add_f32_dpp v144, v144, v144 quad_perm:[2,3,0,1] row_mask:0xf bank_mask:0xf bound_ctrl:1
	ds_read_b64 v[168:169], v61 offset:13856
	ds_read2_b32 v[228:229], v233 offset0:64 offset1:80
	v_add_f32_dpp v144, v144, v144 row_half_mirror row_mask:0xf bank_mask:0xf bound_ctrl:1
	s_waitcnt lgkmcnt(7)
	s_nop 0
	v_add_f32_dpp v144, v144, v144 row_mirror row_mask:0xf bank_mask:0xf bound_ctrl:1
	v_cndmask_b32_e64 v147, v147, v144, s[10:11]
	s_nop 0
	v_mov_b32_dpp v144, v144 row_bcast:15 row_mask:0xa bank_mask:0xf
	v_pk_fma_f32 v[152:153], v[144:145], v[180:181], v[152:153] op_sel_hi:[0,1,1]
	v_mul_f32_e32 v144, v152, v192
	v_mul_f32_e32 v145, v152, v184
	v_fmac_f32_e32 v144, v153, v193
	v_fmac_f32_e32 v145, v153, v185
	v_pk_mul_f32 v[150:151], v[152:153], v[194:195]
	s_nop 0
	v_permlane16_swap_b32_e32 v144, v145
	v_add_f32_e32 v144, v144, v145
	v_pk_fma_f32 v[150:151], v[226:227], v[198:199], v[150:151] op_sel:[0,0,0] op_sel_hi:[0,1,1]
	s_nop 0
	v_add_f32_dpp v144, v144, v144 quad_perm:[1,0,3,2] row_mask:0xf bank_mask:0xf bound_ctrl:1
	ds_read_b128 v[176:179], v61 offset:15360
	ds_read_b128 v[180:183], v61 offset:15376
	v_add_f32_dpp v144, v144, v144 quad_perm:[2,3,0,1] row_mask:0xf bank_mask:0xf bound_ctrl:1
	ds_read_b64 v[184:185], v61 offset:15392
	s_nop 0
	v_add_f32_dpp v144, v144, v144 row_half_mirror row_mask:0xf bank_mask:0xf bound_ctrl:1
	s_waitcnt lgkmcnt(7)
	s_nop 0
	v_add_f32_dpp v144, v144, v144 row_mirror row_mask:0xf bank_mask:0xf bound_ctrl:1
	v_cndmask_b32_e64 v147, v147, v144, s[12:13]
	s_nop 0
	v_mov_b32_dpp v144, v144 row_bcast:15 row_mask:0xa bank_mask:0xf
	v_pk_fma_f32 v[150:151], v[144:145], v[196:197], v[150:151] op_sel_hi:[0,1,1]
	v_mul_f32_e32 v144, v150, v208
	v_mul_f32_e32 v145, v150, v200
	v_fmac_f32_e32 v144, v151, v209
	v_fmac_f32_e32 v145, v151, v201
	v_pk_mul_f32 v[152:153], v[150:151], v[210:211]
	s_nop 0
	v_permlane16_swap_b32_e32 v144, v145
	v_add_f32_e32 v144, v144, v145
	v_pk_fma_f32 v[152:153], v[226:227], v[214:215], v[152:153] op_sel:[1,0,0] op_sel_hi:[1,1,1]
	s_nop 0
	v_add_f32_dpp v144, v144, v144 quad_perm:[1,0,3,2] row_mask:0xf bank_mask:0xf bound_ctrl:1
	ds_read_b128 v[192:195], v61 offset:16896
	ds_read_b128 v[196:199], v61 offset:16912
	v_add_f32_dpp v144, v144, v144 quad_perm:[2,3,0,1] row_mask:0xf bank_mask:0xf bound_ctrl:1
	ds_read_b64 v[200:201], v61 offset:16928
	ds_read2_b32 v[230:231], v233 offset0:96 offset1:112
	v_add_f32_dpp v144, v144, v144 row_half_mirror row_mask:0xf bank_mask:0xf bound_ctrl:1
	s_waitcnt lgkmcnt(7)
; __device__ __forceinline__ float wkv_reduce(float x, float y, float& zy) {
;     auto f = __builtin_amdgcn_permlane16_swap(__float_as_uint(x), __float_as_uint(y), false, false);
;     float z = __uint_as_float(f[0]) + __uint_as_float(f[1]);
;     z += dpp_f(z, 0); z += dpp_f(z, 1); z += dpp_f(z, 2); z += dpp_f(z, 3);
;     zy = z;
;     const int zi = __builtin_bit_cast(int, z);
;     return __builtin_bit_cast(float, __builtin_amdgcn_update_dpp(zi, zi, 0x142, 0xA, 0xF, false));
; }
; __device__ __forceinline__ void wkv_phase(const WkvT& W, unsigned char* lds) {
;     ...
;                 for (int t = 0; t < 32; ++t) {
;                     const f32x2 a2 = {nA[0], nA[1]}, w2 = {nA[2], nA[3]}, b2 = {nB[0], nB[1]}, k2 = {nB[2], nB[3]}, r2 = nr; const float v = nv;
;                     if (t + 1 < 32) { nA = *(const f32x4*)(pp + (t + 1) * 384); nB = *(const f32x4*)(pp + (t + 1) * 384 + 4); nr = *(const f32x2*)(pp + (t + 1) * 384 + 8); nv = pv[(t + 1) * 16]; }
;                     float S0 = S.x, S1 = S.y;
;                     float d = S0 * a2.x; d = __builtin_fmaf(S1, a2.y, d);
;                     float t0 = S0 * w2.x; t0 = __builtin_fmaf(v, k2.x, t0); asm volatile("" : "+v"(t0));
;                     float t1 = S1 * w2.y; t1 = __builtin_fmaf(v, k2.y, t1); asm volatile("" : "+v"(t1));
;                     float yprev; const float sa = wkv_reduce(d, ep, yprev);
;                     S0 = __builtin_fmaf(sa, b2.x, t0); asm volatile("" : "+v"(S0));
;                     S1 = __builtin_fmaf(sa, b2.y, t1); asm volatile("" : "+v"(S1));
;                     ep = S0 * r2.x; ep = __builtin_fmaf(S1, r2.y, ep);
;                     S.x = S0; S.y = S1;
;                     if (t >= 1) { const bool hit = oddrow && ((lane & 15) == ((t - 1) & 15)); if (t <= 16) yk0 = hit ? yprev : yk0; else yk1 = hit ? yprev : yk1; }
	s_nop 0
	v_add_f32_dpp v144, v144, v144 row_mirror row_mask:0xf bank_mask:0xf bound_ctrl:1
	v_cndmask_b32_e64 v147, v147, v144, s[14:15]
	s_nop 0
	v_mov_b32_dpp v144, v144 row_bcast:15 row_mask:0xa bank_mask:0xf
	v_pk_fma_f32 v[152:153], v[144:145], v[212:213], v[152:153] op_sel_hi:[0,1,1]
	v_mul_f32_e32 v144, v152, v160
	v_mul_f32_e32 v145, v152, v216
	v_fmac_f32_e32 v144, v153, v161
	v_fmac_f32_e32 v145, v153, v217
	v_pk_mul_f32 v[150:151], v[152:153], v[162:163]
	s_nop 0
	v_permlane16_swap_b32_e32 v144, v145
	v_add_f32_e32 v144, v144, v145
	v_pk_fma_f32 v[150:151], v[228:229], v[166:167], v[150:151] op_sel:[0,0,0] op_sel_hi:[0,1,1]
	s_nop 0
	v_add_f32_dpp v144, v144, v144 quad_perm:[1,0,3,2] row_mask:0xf bank_mask:0xf bound_ctrl:1
	ds_read_b128 v[208:211], v61 offset:18432
	ds_read_b128 v[212:215], v61 offset:18448
	v_add_f32_dpp v144, v144, v144 quad_perm:[2,3,0,1] row_mask:0xf bank_mask:0xf bound_ctrl:1
	ds_read_b64 v[216:217], v61 offset:18464
	s_nop 0
	v_add_f32_dpp v144, v144, v144 row_half_mirror row_mask:0xf bank_mask:0xf bound_ctrl:1
	s_waitcnt lgkmcnt(7)
	s_nop 0
	v_add_f32_dpp v144, v144, v144 row_mirror row_mask:0xf bank_mask:0xf bound_ctrl:1
	v_cndmask_b32_e64 v147, v147, v144, s[16:17]
	s_nop 0
	v_mov_b32_dpp v144, v144 row_bcast:15 row_mask:0xa bank_mask:0xf
	v_pk_fma_f32 v[150:151], v[144:145], v[164:165], v[150:151] op_sel_hi:[0,1,1]
	v_mul_f32_e32 v144, v150, v176
	v_mul_f32_e32 v145, v150, v168
	v_fmac_f32_e32 v144, v151, v177
	v_fmac_f32_e32 v145, v151, v169
	v_pk_mul_f32 v[152:153], v[150:151], v[178:179]
	s_nop 0
	v_permlane16_swap_b32_e32 v144, v145
	v_add_f32_e32 v144, v144, v145
	v_pk_fma_f32 v[152:153], v[228:229], v[182:183], v[152:153] op_sel:[1,0,0] op_sel_hi:[1,1,1]
	s_nop 0
	v_add_f32_dpp v144, v144, v144 quad_perm:[1,0,3,2] row_mask:0xf bank_mask:0xf bound_ctrl:1
	ds_read_b128 v[160:163], v61 offset:19968
	ds_read_b128 v[164:167], v61 offset:19984
	v_add_f32_dpp v144, v144, v144 quad_perm:[2,3,0,1] row_mask:0xf bank_mask:0xf bound_ctrl:1
	ds_read_b64 v[168:169], v61 offset:20000
	ds_read2_b32 v[224:225], v233 offset0:128 offset1:144
	v_add_f32_dpp v144, v144, v144 row_half_mirror row_mask:0xf bank_mask:0xf bound_ctrl:1
	s_waitcnt lgkmcnt(7)
	s_nop 0
	v_add_f32_dpp v144, v144, v144 row_mirror row_mask:0xf bank_mask:0xf bound_ctrl:1
	v_cndmask_b32_e64 v147, v147, v144, s[18:19]
	s_nop 0
	v_mov_b32_dpp v144, v144 row_bcast:15 row_mask:0xa bank_mask:0xf
	v_pk_fma_f32 v[152:153], v[144:145], v[180:181], v[152:153] op_sel_hi:[0,1,1]
	v_mul_f32_e32 v144, v152, v192
	v_mul_f32_e32 v145, v152, v184
	v_fmac_f32_e32 v144, v153, v193
	v_fmac_f32_e32 v145, v153, v185
	v_pk_mul_f32 v[150:151], v[152:153], v[194:195]
	s_nop 0
	v_permlane16_swap_b32_e32 v144, v145
	v_add_f32_e32 v144, v144, v145
	v_pk_fma_f32 v[150:151], v[230:231], v[198:199], v[150:151] op_sel:[0,0,0] op_sel_hi:[0,1,1]
	s_nop 0
	v_add_f32_dpp v144, v144, v144 quad_perm:[1,0,3,2] row_mask:0xf bank_mask:0xf bound_ctrl:1
	ds_read_b128 v[176:179], v61 offset:21504
	ds_read_b128 v[180:183], v61 offset:21520
	v_add_f32_dpp v144, v144, v144 quad_perm:[2,3,0,1] row_mask:0xf bank_mask:0xf bound_ctrl:1
	ds_read_b64 v[184:185], v61 offset:21536
	s_nop 0
	v_add_f32_dpp v144, v144, v144 row_half_mirror row_mask:0xf bank_mask:0xf bound_ctrl:1
	s_waitcnt lgkmcnt(7)
	s_nop 0
	v_add_f32_dpp v144, v144, v144 row_mirror row_mask:0xf bank_mask:0xf bound_ctrl:1
	v_cndmask_b32_e64 v147, v147, v144, s[20:21]
	s_nop 0
	v_mov_b32_dpp v144, v144 row_bcast:15 row_mask:0xa bank_mask:0xf
	v_pk_fma_f32 v[150:151], v[144:145], v[196:197], v[150:151] op_sel_hi:[0,1,1]
	v_mul_f32_e32 v144, v150, v208
	v_mul_f32_e32 v145, v150, v200
	v_fmac_f32_e32 v144, v151, v209
	v_fmac_f32_e32 v145, v151, v201
	v_pk_mul_f32 v[152:153], v[150:151], v[210:211]
	s_nop 0
	v_permlane16_swap_b32_e32 v144, v145
	v_add_f32_e32 v144, v144, v145
	v_pk_fma_f32 v[152:153], v[230:231], v[214:215], v[152:153] op_sel:[1,0,0] op_sel_hi:[1,1,1]
	s_nop 0
	v_add_f32_dpp v144, v144, v144 quad_perm:[1,0,3,2] row_mask:0xf bank_mask:0xf bound_ctrl:1
	ds_read_b128 v[192:195], v61 offset:23040
	ds_read_b128 v[196:199], v61 offset:23056
	v_add_f32_dpp v144, v144, v144 quad_perm:[2,3,0,1] row_mask:0xf bank_mask:0xf bound_ctrl:1
	ds_read_b64 v[200:201], v61 offset:23072
	ds_read2_b32 v[226:227], v233 offset0:160 offset1:176
	v_add_f32_dpp v144, v144, v144 row_half_mirror row_mask:0xf bank_mask:0xf bound_ctrl:1
	s_waitcnt lgkmcnt(7)
	s_nop 0
	v_add_f32_dpp v144, v144, v144 row_mirror row_mask:0xf bank_mask:0xf bound_ctrl:1
	v_cndmask_b32_e64 v147, v147, v144, s[22:23]
	s_nop 0
	v_mov_b32_dpp v144, v144 row_bcast:15 row_mask:0xa bank_mask:0xf
	v_pk_fma_f32 v[152:153], v[144:145], v[212:213], v[152:153] op_sel_hi:[0,1,1]
	v_mul_f32_e32 v144, v152, v160
	v_mul_f32_e32 v145, v152, v216
	v_fmac_f32_e32 v144, v153, v161
	v_fmac_f32_e32 v145, v153, v217
	v_pk_mul_f32 v[150:151], v[152:153], v[162:163]
	s_nop 0
	v_permlane16_swap_b32_e32 v144, v145
	v_add_f32_e32 v144, v144, v145
	v_pk_fma_f32 v[150:151], v[224:225], v[166:167], v[150:151] op_sel:[0,0,0] op_sel_hi:[0,1,1]
	s_nop 0
	v_add_f32_dpp v144, v144, v144 quad_perm:[1,0,3,2] row_mask:0xf bank_mask:0xf bound_ctrl:1
	ds_read_b128 v[208:211], v61 offset:24576
	ds_read_b128 v[212:215], v61 offset:24592
	v_add_f32_dpp v144, v144, v144 quad_perm:[2,3,0,1] row_mask:0xf bank_mask:0xf bound_ctrl:1
	ds_read_b64 v[216:217], v61 offset:24608
	s_nop 0
	v_add_f32_dpp v144, v144, v144 row_half_mirror row_mask:0xf bank_mask:0xf bound_ctrl:1
	s_waitcnt lgkmcnt(7)
; __device__ __forceinline__ float wkv_reduce(float x, float y, float& zy) {
;     auto f = __builtin_amdgcn_permlane16_swap(__float_as_uint(x), __float_as_uint(y), false, false);
;     float z = __uint_as_float(f[0]) + __uint_as_float(f[1]);
;     z += dpp_f(z, 0); z += dpp_f(z, 1); z += dpp_f(z, 2); z += dpp_f(z, 3);
;     zy = z;
;     const int zi = __builtin_bit_cast(int, z);
;     return __builtin_bit_cast(float, __builtin_amdgcn_update_dpp(zi, zi, 0x142, 0xA, 0xF, false));
; }
; __device__ __forceinline__ void wkv_phase(const WkvT& W, unsigned char* lds) {
;     ...
;                 for (int t = 0; t < 32; ++t) {
;                     const f32x2 a2 = {nA[0], nA[1]}, w2 = {nA[2], nA[3]}, b2 = {nB[0], nB[1]}, k2 = {nB[2], nB[3]}, r2 = nr; const float v = nv;
;                     if (t + 1 < 32) { nA = *(const f32x4*)(pp + (t + 1) * 384); nB = *(const f32x4*)(pp + (t + 1) * 384 + 4); nr = *(const f32x2*)(pp + (t + 1) * 384 + 8); nv = pv[(t + 1) * 16]; }
;                     float S0 = S.x, S1 = S.y;
;                     float d = S0 * a2.x; d = __builtin_fmaf(S1, a2.y, d);
;                     float t0 = S0 * w2.x; t0 = __builtin_fmaf(v, k2.x, t0); asm volatile("" : "+v"(t0));
;                     float t1 = S1 * w2.y; t1 = __builtin_fmaf(v, k2.y, t1); asm volatile("" : "+v"(t1));
;                     float yprev; const float sa = wkv_reduce(d, ep, yprev);
;                     S0 = __builtin_fmaf(sa, b2.x, t0); asm volatile("" : "+v"(S0));
;                     S1 = __builtin_fmaf(sa, b2.y, t1); asm volatile("" : "+v"(S1));
;                     ep = S0 * r2.x; ep = __builtin_fmaf(S1, r2.y, ep);
;                     S.x = S0; S.y = S1;
;                     if (t >= 1) { const bool hit = oddrow && ((lane & 15) == ((t - 1) & 15)); if (t <= 16) yk0 = hit ? yprev : yk0; else yk1 = hit ? yprev : yk1; }
	s_nop 0
	v_add_f32_dpp v144, v144, v144 row_mirror row_mask:0xf bank_mask:0xf bound_ctrl:1
	v_cndmask_b32_e64 v147, v147, v144, s[24:25]
	s_nop 0
	v_mov_b32_dpp v144, v144 row_bcast:15 row_mask:0xa bank_mask:0xf
	v_pk_fma_f32 v[150:151], v[144:145], v[164:165], v[150:151] op_sel_hi:[0,1,1]
	v_mul_f32_e32 v144, v150, v176
	v_mul_f32_e32 v145, v150, v168
	v_fmac_f32_e32 v144, v151, v177
	v_fmac_f32_e32 v145, v151, v169
	v_pk_mul_f32 v[152:153], v[150:151], v[178:179]
	s_nop 0
	v_permlane16_swap_b32_e32 v144, v145
	v_add_f32_e32 v144, v144, v145
	v_pk_fma_f32 v[152:153], v[224:225], v[182:183], v[152:153] op_sel:[1,0,0] op_sel_hi:[1,1,1]
	s_nop 0
	v_add_f32_dpp v144, v144, v144 quad_perm:[1,0,3,2] row_mask:0xf bank_mask:0xf bound_ctrl:1
	ds_read_b128 v[160:163], v61 offset:26112
	ds_read_b128 v[164:167], v61 offset:26128
	v_add_f32_dpp v144, v144, v144 quad_perm:[2,3,0,1] row_mask:0xf bank_mask:0xf bound_ctrl:1
	ds_read_b64 v[168:169], v61 offset:26144
	ds_read2_b32 v[228:229], v233 offset0:192 offset1:208
	v_add_f32_dpp v144, v144, v144 row_half_mirror row_mask:0xf bank_mask:0xf bound_ctrl:1
	s_waitcnt lgkmcnt(7)
	s_nop 0
	v_add_f32_dpp v144, v144, v144 row_mirror row_mask:0xf bank_mask:0xf bound_ctrl:1
	v_cndmask_b32_e64 v147, v147, v144, s[26:27]
	s_nop 0
	v_mov_b32_dpp v144, v144 row_bcast:15 row_mask:0xa bank_mask:0xf
	v_pk_fma_f32 v[152:153], v[144:145], v[180:181], v[152:153] op_sel_hi:[0,1,1]
	v_mul_f32_e32 v144, v152, v192
	v_mul_f32_e32 v145, v152, v184
	v_fmac_f32_e32 v144, v153, v193
	v_fmac_f32_e32 v145, v153, v185
	v_pk_mul_f32 v[150:151], v[152:153], v[194:195]
	s_nop 0
	v_permlane16_swap_b32_e32 v144, v145
	v_add_f32_e32 v144, v144, v145
	v_pk_fma_f32 v[150:151], v[226:227], v[198:199], v[150:151] op_sel:[0,0,0] op_sel_hi:[0,1,1]
	s_nop 0
	v_add_f32_dpp v144, v144, v144 quad_perm:[1,0,3,2] row_mask:0xf bank_mask:0xf bound_ctrl:1
	ds_read_b128 v[176:179], v61 offset:27648
	ds_read_b128 v[180:183], v61 offset:27664
	v_add_f32_dpp v144, v144, v144 quad_perm:[2,3,0,1] row_mask:0xf bank_mask:0xf bound_ctrl:1
	ds_read_b64 v[184:185], v61 offset:27680
	s_nop 0
	v_add_f32_dpp v144, v144, v144 row_half_mirror row_mask:0xf bank_mask:0xf bound_ctrl:1
	s_waitcnt lgkmcnt(7)
	s_nop 0
	v_add_f32_dpp v144, v144, v144 row_mirror row_mask:0xf bank_mask:0xf bound_ctrl:1
	v_cndmask_b32_e64 v147, v147, v144, s[28:29]
	s_nop 0
	v_mov_b32_dpp v144, v144 row_bcast:15 row_mask:0xa bank_mask:0xf
	v_pk_fma_f32 v[150:151], v[144:145], v[196:197], v[150:151] op_sel_hi:[0,1,1]
	v_mul_f32_e32 v144, v150, v208
	v_mul_f32_e32 v145, v150, v200
	v_fmac_f32_e32 v144, v151, v209
	v_fmac_f32_e32 v145, v151, v201
	v_pk_mul_f32 v[152:153], v[150:151], v[210:211]
	s_nop 0
	v_permlane16_swap_b32_e32 v144, v145
	v_add_f32_e32 v144, v144, v145
	v_pk_fma_f32 v[152:153], v[226:227], v[214:215], v[152:153] op_sel:[1,0,0] op_sel_hi:[1,1,1]
	s_nop 0
	v_add_f32_dpp v144, v144, v144 quad_perm:[1,0,3,2] row_mask:0xf bank_mask:0xf bound_ctrl:1
	ds_read_b128 v[192:195], v61 offset:29184
	ds_read_b128 v[196:199], v61 offset:29200
	v_add_f32_dpp v144, v144, v144 quad_perm:[2,3,0,1] row_mask:0xf bank_mask:0xf bound_ctrl:1
	ds_read_b64 v[200:201], v61 offset:29216
	ds_read2_b32 v[230:231], v233 offset0:224 offset1:240
	v_add_f32_dpp v144, v144, v144 row_half_mirror row_mask:0xf bank_mask:0xf bound_ctrl:1
	s_waitcnt lgkmcnt(7)
	s_nop 0
	v_add_f32_dpp v144, v144, v144 row_mirror row_mask:0xf bank_mask:0xf bound_ctrl:1
	v_cndmask_b32_e64 v147, v147, v144, s[30:31]
	s_nop 0
	v_mov_b32_dpp v144, v144 row_bcast:15 row_mask:0xa bank_mask:0xf
	v_pk_fma_f32 v[152:153], v[144:145], v[212:213], v[152:153] op_sel_hi:[0,1,1]
	v_mul_f32_e32 v144, v152, v160
	v_mul_f32_e32 v145, v152, v216
	v_fmac_f32_e32 v144, v153, v161
	v_fmac_f32_e32 v145, v153, v217
	v_pk_mul_f32 v[150:151], v[152:153], v[162:163]
	s_nop 0
	v_permlane16_swap_b32_e32 v144, v145
	v_add_f32_e32 v144, v144, v145
	v_pk_fma_f32 v[150:151], v[228:229], v[166:167], v[150:151] op_sel:[0,0,0] op_sel_hi:[0,1,1]
	s_nop 0
	v_add_f32_dpp v144, v144, v144 quad_perm:[1,0,3,2] row_mask:0xf bank_mask:0xf bound_ctrl:1
	ds_read_b128 v[208:211], v61 offset:30720
	ds_read_b128 v[212:215], v61 offset:30736
	v_add_f32_dpp v144, v144, v144 quad_perm:[2,3,0,1] row_mask:0xf bank_mask:0xf bound_ctrl:1
	ds_read_b64 v[216:217], v61 offset:30752
	s_nop 0
	v_add_f32_dpp v144, v144, v144 row_half_mirror row_mask:0xf bank_mask:0xf bound_ctrl:1
	s_waitcnt lgkmcnt(7)
	s_nop 0
	v_add_f32_dpp v144, v144, v144 row_mirror row_mask:0xf bank_mask:0xf bound_ctrl:1
	v_cndmask_b32_e64 v147, v147, v144, s[34:35]
	s_nop 0
	v_mov_b32_dpp v144, v144 row_bcast:15 row_mask:0xa bank_mask:0xf
	v_pk_fma_f32 v[150:151], v[144:145], v[164:165], v[150:151] op_sel_hi:[0,1,1]
	v_mul_f32_e32 v144, v150, v176
	v_mul_f32_e32 v145, v150, v168
	v_fmac_f32_e32 v144, v151, v177
	v_fmac_f32_e32 v145, v151, v169
	v_pk_mul_f32 v[152:153], v[150:151], v[178:179]
	s_nop 0
	v_permlane16_swap_b32_e32 v144, v145
	v_add_f32_e32 v144, v144, v145
	v_pk_fma_f32 v[152:153], v[228:229], v[182:183], v[152:153] op_sel:[1,0,0] op_sel_hi:[1,1,1]
	s_nop 0
	v_add_f32_dpp v144, v144, v144 quad_perm:[1,0,3,2] row_mask:0xf bank_mask:0xf bound_ctrl:1
	s_nop 1
	v_add_f32_dpp v144, v144, v144 quad_perm:[2,3,0,1] row_mask:0xf bank_mask:0xf bound_ctrl:1
	s_nop 1
	v_add_f32_dpp v144, v144, v144 row_half_mirror row_mask:0xf bank_mask:0xf bound_ctrl:1
	s_waitcnt lgkmcnt(3)
; __device__ __forceinline__ void wkv_phase(const WkvT& W, unsigned char* lds) {
;     ...
;                 for (int t = 0; t < 32; ++t) {
;                     const f32x2 a2 = {nA[0], nA[1]}, w2 = {nA[2], nA[3]}, b2 = {nB[0], nB[1]}, k2 = {nB[2], nB[3]}, r2 = nr; const float v = nv;
;                     if (t + 1 < 32) { nA = *(const f32x4*)(pp + (t + 1) * 384); nB = *(const f32x4*)(pp + (t + 1) * 384 + 4); nr = *(const f32x2*)(pp + (t + 1) * 384 + 8); nv = pv[(t + 1) * 16]; }
;                     float S0 = S.x, S1 = S.y;
;                     float d = S0 * a2.x; d = __builtin_fmaf(S1, a2.y, d);
;                     float t0 = S0 * w2.x; t0 = __builtin_fmaf(v, k2.x, t0); asm volatile("" : "+v"(t0));
;                     float t1 = S1 * w2.y; t1 = __builtin_fmaf(v, k2.y, t1); asm volatile("" : "+v"(t1));
;                     float yprev; const float sa = wkv_reduce(d, ep, yprev);
;                     S0 = __builtin_fmaf(sa, b2.x, t0); asm volatile("" : "+v"(S0));
;                     S1 = __builtin_fmaf(sa, b2.y, t1); asm volatile("" : "+v"(S1));
;                     ep = S0 * r2.x; ep = __builtin_fmaf(S1, r2.y, ep);
;                     S.x = S0; S.y = S1;
;                     if (t >= 1) { const bool hit = oddrow && ((lane & 15) == ((t - 1) & 15)); if (t <= 16) yk0 = hit ? yprev : yk0; else yk1 = hit ? yprev : yk1; }
;                 }
;                 { float ylast; (void)wkv_reduce(0.f, ep, ylast); yk1 = (oddrow && (lane & 15) == 15) ? ylast : yk1; }
;                 if (oddrow) { sY[bi * 512 + (lane & 15) * 16 + il] = yk0; sY[bi * 512 + (16 + (lane & 15)) * 16 + il] = yk1; }
	s_nop 0
	v_add_f32_dpp v144, v144, v144 row_mirror row_mask:0xf bank_mask:0xf bound_ctrl:1
	v_cndmask_b32_e64 v147, v147, v144, s[36:37]
	s_nop 0
	v_mov_b32_dpp v144, v144 row_bcast:15 row_mask:0xa bank_mask:0xf
	v_pk_fma_f32 v[152:153], v[144:145], v[180:181], v[152:153] op_sel_hi:[0,1,1]
	v_mul_f32_e32 v144, v152, v192
	v_mul_f32_e32 v145, v152, v184
	v_fmac_f32_e32 v144, v153, v193
	v_fmac_f32_e32 v145, v153, v185
	v_pk_mul_f32 v[150:151], v[152:153], v[194:195]
	s_nop 0
	v_permlane16_swap_b32_e32 v144, v145
	v_add_f32_e32 v144, v144, v145
	v_pk_fma_f32 v[150:151], v[230:231], v[198:199], v[150:151] op_sel:[0,0,0] op_sel_hi:[0,1,1]
	s_nop 0
	v_add_f32_dpp v144, v144, v144 quad_perm:[1,0,3,2] row_mask:0xf bank_mask:0xf bound_ctrl:1
	s_nop 1
	v_add_f32_dpp v144, v144, v144 quad_perm:[2,3,0,1] row_mask:0xf bank_mask:0xf bound_ctrl:1
	s_nop 1
	v_add_f32_dpp v144, v144, v144 row_half_mirror row_mask:0xf bank_mask:0xf bound_ctrl:1
	s_waitcnt lgkmcnt(0)
	s_nop 0
	v_add_f32_dpp v144, v144, v144 row_mirror row_mask:0xf bank_mask:0xf bound_ctrl:1
	v_cndmask_b32_e64 v147, v147, v144, s[38:39]
	s_nop 0
	v_mov_b32_dpp v144, v144 row_bcast:15 row_mask:0xa bank_mask:0xf
	v_pk_fma_f32 v[150:151], v[144:145], v[196:197], v[150:151] op_sel_hi:[0,1,1]
	v_mul_f32_e32 v144, v150, v208
	v_mul_f32_e32 v145, v150, v200
	v_fmac_f32_e32 v144, v151, v209
	v_fmac_f32_e32 v145, v151, v201
	v_pk_mul_f32 v[140:141], v[150:151], v[210:211]
	s_nop 0
	v_permlane16_swap_b32_e32 v144, v145
	v_add_f32_e32 v144, v144, v145
	v_pk_fma_f32 v[140:141], v[230:231], v[214:215], v[140:141] op_sel:[1,0,0] op_sel_hi:[1,1,1]
	s_nop 0
	v_add_f32_dpp v144, v144, v144 quad_perm:[1,0,3,2] row_mask:0xf bank_mask:0xf bound_ctrl:1
	s_nop 1
	v_add_f32_dpp v144, v144, v144 quad_perm:[2,3,0,1] row_mask:0xf bank_mask:0xf bound_ctrl:1
	s_nop 1
	v_add_f32_dpp v144, v144, v144 row_half_mirror row_mask:0xf bank_mask:0xf bound_ctrl:1
	s_nop 1
	v_add_f32_dpp v144, v144, v144 row_mirror row_mask:0xf bank_mask:0xf bound_ctrl:1
	v_cndmask_b32_e64 v147, v147, v144, s[40:41]
	s_nop 0
	v_mov_b32_dpp v144, v144 row_bcast:15 row_mask:0xa bank_mask:0xf
	v_pk_fma_f32 v[140:141], v[144:145], v[212:213], v[140:141] op_sel_hi:[0,1,1]
	v_mul_f32_e32 v145, v140, v216
	v_fmac_f32_e32 v145, v141, v217
	s_nop 1
	v_permlane16_swap_b32_e32 v148, v145
	v_add_f32_e32 v145, v148, v145
	s_nop 1
	v_add_f32_dpp v145, v145, v145 quad_perm:[1,0,3,2] row_mask:0xf bank_mask:0xf bound_ctrl:1
	s_nop 1
	v_add_f32_dpp v145, v145, v145 quad_perm:[2,3,0,1] row_mask:0xf bank_mask:0xf bound_ctrl:1
	s_nop 1
	v_add_f32_dpp v145, v145, v145 row_half_mirror row_mask:0xf bank_mask:0xf bound_ctrl:1
	s_nop 1
	v_add_f32_dpp v145, v145, v145 row_mirror row_mask:0xf bank_mask:0xf bound_ctrl:1
	v_cndmask_b32_e64 v147, v147, v145, s[6:7]
	s_and_saveexec_b64 s[96:97], s[4:5]
	ds_write2st64_b32 v29, v146, v147 offset0:8 offset1:12
; __device__ __forceinline__ void wkv_stage(const WkvT& W, const WkvRaw& raw, size_t rowbase, int h, int q, int c, int tid, const float (&kkc)[4], const float (&kac)[4], const float (&rkc)[4],
;                                           float* sP, float* sV) {
;     const float r[4] = {bflo(raw.r[0]), bfhi(raw.r[0]), bflo(raw.r[1]), bfhi(raw.r[1])}, k[4] = {bflo(raw.k[0]), bfhi(raw.k[0]), bflo(raw.k[1]), bfhi(raw.k[1])};
;     const float a[4] = {bflo(raw.a[0]), bfhi(raw.a[0]), bflo(raw.a[1]), bfhi(raw.a[1])}, l[4] = {bflo(raw.l[0]), bfhi(raw.l[0]), bflo(raw.l[1]), bfhi(raw.l[1])};
;     float kkr[4], km[4], n2 = 0.f, bs = 0.f;
; #pragma unroll
;     for (int e = 0; e < 4; ++e) { kkr[e] = k[e] * kkc[e]; n2 += kkr[e] * kkr[e]; km[e] = k[e] * (1.f + (a[e] - 1.f) * kac[e]); bs += r[e] * km[e] * rkc[e]; }
;     n2 = row16_sum(n2); bs = row16_sum(bs);
;     const float inv = __builtin_amdgcn_rcpf(fmaxf(sqrtf(n2), 1e-12f));
;     const int t = tid >> 4;
;     float* rec = sP + (t * 32 + 2 * (tid & 15)) * 12;
; #pragma unroll
;     for (int hlf = 0; hlf < 2; ++hlf) { const int e = 2 * hlf; float* rp = rec + hlf * 12;
;         *(f32x4*)(rp) = (f32x4){-kkr[e] * inv, -kkr[e + 1] * inv, __builtin_amdgcn_exp2f(LOG2E_ * l[e]), __builtin_amdgcn_exp2f(LOG2E_ * l[e + 1])};
;         *(f32x4*)(rp + 4) = (f32x4){kkr[e] * inv * a[e], kkr[e + 1] * inv * a[e + 1], km[e], km[e + 1]};
;         *(f32x2*)(rp + 8) = (f32x2){r[e], r[e + 1]}; }
;     if ((tid & 15) < 4) *(f32x4*)(sV + t * 16 + 4 * (tid & 15)) = (f32x4){bflo(raw.v[0]), bfhi(raw.v[0]), bflo(raw.v[1]), bfhi(raw.v[1])};
;     if (q == 0 && (tid & 15) == 0) W.bonus[(rowbase + (size_t)c * 32 + t) * 32 + h] = bs;
; __device__ __forceinline__ void wkv_phase(const WkvT& W, unsigned char* lds) {
;     ...
;             if (c + 1 < 256) wkv_stage(W, raw, rowbase, h, q, c + 1, tid, kkc, kac, rkc, sP + bn, sV + (bi ^ 1) * 512);
;             lds_barrier();
;             {
;                 const int t = tid >> 4, i = tid & 15; const float yv = sY[bi * 512 + t * 16 + i];
;                 const size_t row = rowbase + (size_t)c * 32 + t;
;                 W.Y[row * DM + cbase + q * 16 + i] = f2bf(yv);
;                 const float s1 = row16_sum(yv), s2 = row16_sum(yv * yv);
;                 if (i == 0) *(f32x2*)(W.stats + ((row * 32 + h) * 4 + q) * 2) = (f32x2){s1, s2};
;             }
.LBB0_1638:
	s_or_b64 exec, exec, s[96:97]
	s_andn2_b64 vcc, exec, s[46:47]
	s_cbranch_vccnz .LBB0_1644
	s_waitcnt vmcnt(2)
	v_lshlrev_b32_e32 v130, 16, v52
	v_and_b32_e32 v131, 0xffff0000, v52
	v_and_b32_e32 v59, 0xffff0000, v53
	v_lshlrev_b32_e32 v58, 16, v53
	v_pk_mul_f32 v[52:53], v[6:7], v[130:131]
	v_pk_mul_f32 v[126:127], v[8:9], v[58:59]
	v_pk_mul_f32 v[132:133], v[52:53], v[52:53]
	v_pk_mul_f32 v[128:129], v[126:127], v[126:127]
	v_add_f32_e32 v16, v132, v133
	v_add_f32_e32 v16, v128, v16
	v_add_f32_e32 v16, v129, v16
	v_lshlrev_b32_e32 v54, 16, v50
	v_and_b32_e32 v55, 0xffff0000, v50
	v_add_f32_dpp v16, v16, v16 quad_perm:[1,0,3,2] row_mask:0xf bank_mask:0xf bound_ctrl:1
	v_lshlrev_b32_e32 v56, 16, v51
	v_and_b32_e32 v57, 0xffff0000, v51
	v_add_f32_dpp v16, v16, v16 quad_perm:[2,3,0,1] row_mask:0xf bank_mask:0xf bound_ctrl:1
	s_waitcnt vmcnt(0)
	v_lshlrev_b32_e32 v51, 16, v48
	v_and_b32_e32 v48, 0xffff0000, v48
	v_add_f32_dpp v16, v16, v16 row_half_mirror row_mask:0xf bank_mask:0xf bound_ctrl:1
	s_nop 1
	v_add_f32_dpp v16, v16, v16 row_mirror row_mask:0xf bank_mask:0xf bound_ctrl:1
	v_mul_f32_e32 v50, 0x4f800000, v16
	v_cmp_gt_f32_e32 vcc, s3, v16
	s_nop 1
	v_cndmask_b32_e32 v16, v16, v50, vcc
	v_sqrt_f32_e32 v50, v16
	s_nop 0
	v_add_u32_e32 v128, -1, v50
	v_fma_f32 v129, -v128, v50, v16
	v_cmp_ge_f32_e64 s[46:47], 0, v129
	v_add_u32_e32 v129, 1, v50
	s_nop 0
	v_cndmask_b32_e64 v128, v50, v128, s[46:47]
	v_fma_f32 v50, -v129, v50, v16
	v_cmp_lt_f32_e64 s[46:47], 0, v50
	s_nop 1
	v_cndmask_b32_e64 v50, v128, v129, s[46:47]
	v_mul_f32_e32 v128, 0x37800000, v50
	v_cndmask_b32_e32 v50, v50, v128, vcc
	v_cmp_class_f32_e32 vcc, v16, v124
	v_and_b32_e32 v129, 0xffff0000, v49
	s_nop 0
	v_cndmask_b32_e32 v16, v50, v16, vcc
	v_max_f32_e32 v16, 0x2b8cbccc, v16
	v_rcp_f32_e32 v128, v16
	v_mul_f32_e32 v16, 0x3fb8aa3b, v51
	v_exp_f32_e32 v50, v16
	v_mul_f32_e32 v16, 0x3fb8aa3b, v48
	v_exp_f32_e32 v51, v16
	v_lshlrev_b32_e32 v16, 16, v49
	v_pk_mul_f32 v[48:49], v[128:129], v[52:53] op_sel_hi:[0,1] neg_lo:[0,1] neg_hi:[0,1]
	v_mul_f32_e32 v16, 0x3fb8aa3b, v16
	ds_write_b128 v125, v[48:51]
	v_lshlrev_b32_e32 v48, 16, v46
	v_and_b32_e32 v49, 0xffff0000, v46
	v_pk_add_f32 v[50:51], v[48:49], -1.0 op_sel_hi:[1,0]
	s_nop 0
	v_pk_fma_f32 v[50:51], v[10:11], v[50:51], 1.0 op_sel_hi:[1,1,0]
	s_nop 0
	v_pk_mul_f32 v[50:51], v[50:51], v[130:131]
	v_pk_mul_f32 v[130:131], v[52:53], v[128:129] op_sel_hi:[1,0]
	v_exp_f32_e32 v52, v16
	v_mul_f32_e32 v16, 0x3fb8aa3b, v129
	v_mul_f32_e32 v46, v50, v54
	v_exp_f32_e32 v53, v16
	v_pk_mul_f32 v[48:49], v[130:131], v[48:49]
	v_fma_f32 v132, v2, v46, 0
	v_mul_f32_e32 v46, v51, v55
	ds_write_b128 v125, v[48:51] offset:16
	v_lshlrev_b32_e32 v48, 16, v47
	v_and_b32_e32 v49, 0xffff0000, v47
	v_fmac_f32_e32 v132, v3, v46
	v_pk_add_f32 v[46:47], v[48:49], -1.0 op_sel_hi:[1,0]
	v_pk_mul_f32 v[50:51], v[128:129], v[126:127] op_sel_hi:[0,1] neg_lo:[0,1] neg_hi:[0,1]
	v_pk_fma_f32 v[46:47], v[12:13], v[46:47], 1.0 op_sel_hi:[1,1,0]
	ds_write_b128 v125, v[50:53] offset:48
	v_pk_mul_f32 v[50:51], v[46:47], v[58:59]
	v_pk_mul_f32 v[52:53], v[126:127], v[128:129] op_sel_hi:[1,0]
	v_mul_f32_e32 v16, v50, v56
	v_mul_f32_e32 v46, v51, v57
	v_fmac_f32_e32 v132, v4, v16
	v_fmac_f32_e32 v132, v5, v46
	v_pk_mul_f32 v[48:49], v[52:53], v[48:49]
	ds_write_b128 v125, v[48:51] offset:64
	ds_write2_b64 v125, v[54:55], v[56:57] offset0:4 offset1:10
	v_add_f32_dpp v16, v132, v132 quad_perm:[1,0,3,2] row_mask:0xf bank_mask:0xf bound_ctrl:1
	s_nop 1
	v_add_f32_dpp v16, v16, v16 quad_perm:[2,3,0,1] row_mask:0xf bank_mask:0xf bound_ctrl:1
	s_nop 1
	v_add_f32_dpp v16, v16, v16 row_half_mirror row_mask:0xf bank_mask:0xf bound_ctrl:1
	s_nop 1
	v_mov_b32_dpp v46, v16 row_mirror row_mask:0xf bank_mask:0xf bound_ctrl:1
	s_and_saveexec_b64 s[46:47], s[0:1]
	v_lshlrev_b32_e32 v48, 16, v32
	v_and_b32_e32 v49, 0xffff0000, v32
	v_lshlrev_b32_e32 v50, 16, v33
	v_and_b32_e32 v51, 0xffff0000, v33
	ds_write_b128 v15, v[48:51]
	s_or_b64 exec, exec, s[46:47]
	s_and_saveexec_b64 s[46:47], s[42:43]
	s_cbranch_execz .LBB0_1643
	v_add_f32_e32 v16, v16, v46
	v_lshl_add_u64 v[46:47], s[52:53], 0, v[38:39]
	v_add_co_u32_e32 v46, vcc, 0x1e502000, v46
	s_nop 1
	v_addc_co_u32_e32 v47, vcc, 0, v47, vcc
	global_store_dword v[46:47], v16, off
.LBB0_1643:
	s_or_b64 exec, exec, s[46:47]
.LBB0_1644:
	s_waitcnt lgkmcnt(0)
	s_barrier
	s_waitcnt vmcnt(1)
	ds_read_b32 v46, v60 offset:2048
	s_waitcnt vmcnt(0)
	v_lshl_add_u64 v[48:49], s[52:53], 0, v[36:37]
	s_waitcnt lgkmcnt(0)
	v_mul_f32_e32 v47, v46, v46
	v_mov_b32_dpp v50, v46 quad_perm:[1,0,3,2] row_mask:0xf bank_mask:0xf bound_ctrl:1
	s_nop 0
	v_mov_b32_dpp v51, v47 quad_perm:[1,0,3,2] row_mask:0xf bank_mask:0xf bound_ctrl:1
	v_cvt_pk_bf16_f32 v16, v46, s0
	v_pk_add_f32 v[46:47], v[46:47], v[50:51]
	global_store_short v[48:49], v16, off
	s_nop 0
	v_mov_b32_dpp v48, v46 quad_perm:[2,3,0,1] row_mask:0xf bank_mask:0xf bound_ctrl:1
	v_mov_b32_dpp v49, v47 quad_perm:[2,3,0,1] row_mask:0xf bank_mask:0xf bound_ctrl:1
	v_pk_add_f32 v[46:47], v[46:47], v[48:49]
	s_nop 1
	v_mov_b32_dpp v48, v46 row_half_mirror row_mask:0xf bank_mask:0xf bound_ctrl:1
	v_mov_b32_dpp v49, v47 row_half_mirror row_mask:0xf bank_mask:0xf bound_ctrl:1
	v_pk_add_f32 v[46:47], v[46:47], v[48:49]
	s_nop 1
	v_mov_b32_dpp v48, v46 row_mirror row_mask:0xf bank_mask:0xf bound_ctrl:1
	v_mov_b32_dpp v49, v47 row_mirror row_mask:0xf bank_mask:0xf bound_ctrl:1
	s_and_saveexec_b64 s[46:47], s[8:9]
	s_cbranch_execz .LBB0_1621
	v_pk_add_f32 v[46:47], v[46:47], v[48:49]
	v_lshl_add_u64 v[48:49], s[52:53], 0, v[34:35]
	v_add_co_u32_e32 v48, vcc, 0x1d508000, v48
	s_nop 1
	v_addc_co_u32_e32 v49, vcc, 0, v49, vcc
	global_store_dwordx2 v[48:49], v[46:47], off
	s_branch .LBB0_1621
